# P1: half-tile mode for the under-filled last round (97 tiles split into row halves over 194 workgroups; the other half's MFMA blocks and epilogue groups skipped)
# speedup vs baseline: 1.0102x; 1.0102x over previous
;     __host__ __device__ bool next(int i, Unit& u) const {
;         const long L = (long)i * G + c; if (L >= nwg) return false;
;         int wgid = (int)L; { const int q = nwg / NXCD, r = nwg % NXCD, xcd = wgid % NXCD, off = wgid / NXCD; wgid = (xcd < r ? xcd * (q + 1) : r * (q + 1) + (xcd - r) * q) + off; }
;         const int nig = WGM * nN, gid = wgid / nig, fm = gid * WGM, gsz = (nM - fm) < WGM ? (nM - fm) : WGM;
;         u.pm = fm + ((wgid % nig) % gsz); u.pn = (wgid % nig) / gsz; return true;
; template <class Epi, class Sched, bool ALIGN_EPI = false, bool SP2 = false>
; __device__ __forceinline__ void gemm_phase(PG8_LAS unsigned char* lds, const Gemm g, const Sched& S, const Epi& E) {
;     ...
;         const bool has_next = S.next(ui + 1, nxt);
;         const char* nA = has_next ? (const char*)g.A + (size_t)nxt.pm * tstepA : cA; const char* nB = has_next ? (const char*)g.Bt + (size_t)nxt.pn * tstepB : cB;
.LBB0_122:
	s_andn2_b64 vcc, exec, s[12:13]
	s_mov_b32 s48, s28
	s_mov_b32 s18, s30
	s_mov_b64 s[12:13], s[36:37]
	s_mov_b64 s[42:43], s[20:21]
	s_mov_b32 s100, s101
	s_cbranch_vccz .LBB0_320
.LBB0_123:
	s_add_i32 s26, s26, 1
	v_readlane_b32 s1, v252, 26
	v_readlane_b32 s10, v253, 1
	s_mul_i32 s1, s26, s1
	s_mul_hi_u32 s4, s26, s10
	s_add_i32 s4, s4, s1
	s_mul_i32 s1, s26, s10
	v_readlane_b32 s10, v252, 0
	s_add_u32 s20, s1, s10
	v_readlane_b32 s1, v252, 24
	s_addc_u32 s21, s4, s1
	s_mov_b32 s101, 0
	s_cmp_eq_u32 s26, 8
	s_cbranch_scc0 .Lh_sched_done
	v_readlane_b32 s98, v253, 1
	s_cmp_eq_u32 s98, 0x100
	s_cbranch_scc0 .Lh_sched_done
	s_cmp_lt_u32 s10, 97
	s_cselect_b32 s101, 1, 0
	s_cbranch_scc1 .Lh_sched_done
	s_sub_u32 s98, s10, 0x80
	s_cmp_lt_u32 s98, 97
	s_cbranch_scc0 .Lh_sched_done
	s_sub_u32 s20, s20, 0x80
	s_subb_u32 s21, s21, 0
	s_mov_b32 s101, 2
.Lh_sched_done:
	v_cmp_gt_i64_e32 vcc, s[20:21], v[146:147]
	v_cmp_lt_i64_e64 s[40:41], s[20:21], v[144:145]
	s_cbranch_vccnz .LBB0_129
	s_ashr_i32 s1, s20, 31
	s_lshr_b32 s1, s1, 29
	s_add_i32 s1, s20, s1
	s_and_b32 s4, s1, -8
	s_sub_i32 s4, s20, s4
	s_cmp_gt_i32 s4, 0
	s_mov_b64 s[20:21], -1
	s_cbranch_scc0 .LBB0_126
	s_mul_i32 s10, s4, 0x10c
	s_or_b32 s10, s10, 1
	s_mov_b64 s[20:21], 0

;     __host__ __device__ bool next(int i, Unit& u) const {
;     ...
;         int wgid = (int)L; { const int q = nwg / NXCD, r = nwg % NXCD, xcd = wgid % NXCD, off = wgid / NXCD; wgid = (xcd < r ? xcd * (q + 1) : r * (q + 1) + (xcd - r) * q) + off; }
;         const int nig = WGM * nN, gid = wgid / nig, fm = gid * WGM, gsz = (nM - fm) < WGM ? (nM - fm) : WGM;
;         u.pm = fm + ((wgid % nig) % gsz); u.pn = (wgid % nig) / gsz; return true;
; template <class Epi, class Sched, bool ALIGN_EPI = false, bool SP2 = false>
; __device__ __forceinline__ void gemm_phase(PG8_LAS unsigned char* lds, const Gemm g, const Sched& S, const Epi& E) {
;     ...
; #pragma unroll
;         for (int a = 0; a < 2; ++a)
; #pragma unroll
;             for (int b = 0; b < 2; ++b)
; #pragma unroll
;                 for (int m = 0; m < 4; ++m)
; #pragma unroll
;                     for (int n = 0; n < 2; ++n) acc[a][b][m][n] = (f32x4){0.f, 0.f, 0.f, 0.f};
;         cur = nxt; cA = nA; cB = nB; ++ui;
.LBB0_128:
	s_ashr_i32 s1, s1, 3
	s_add_i32 s1, s10, s1
	s_mul_hi_i32 s4, s1, 0x3e0f83e1
	s_lshr_b32 s10, s4, 31
	s_ashr_i32 s4, s4, 6
	s_add_i32 s4, s4, s10
	s_lshl_b32 s10, s4, 3
	s_sub_i32 s11, 0x41, s10
	s_min_i32 s11, s11, 8
	s_abs_i32 s14, s11
	v_cvt_f32_u32_e32 v0, s14
	s_sub_i32 s19, 0, s14
	s_mulk_i32 s4, 0x108
	s_sub_i32 s1, s1, s4
	v_rcp_iflag_f32_e32 v0, v0
	s_abs_i32 s4, s1
	s_xor_b32 s15, s1, s11
	s_ashr_i32 s15, s15, 31
	v_mul_f32_e32 v0, 0x4f7ffffe, v0
	v_cvt_u32_f32_e32 v0, v0
	s_nop 0
	v_readfirstlane_b32 s20, v0
	s_mul_i32 s19, s19, s20
	s_mul_hi_u32 s19, s20, s19
	s_add_i32 s20, s20, s19
	s_mul_hi_u32 s19, s4, s20
	s_mul_i32 s20, s19, s14
	s_sub_i32 s4, s4, s20
	s_add_i32 s21, s19, 1
	s_sub_i32 s20, s4, s14
	s_cmp_ge_u32 s4, s14
	s_cselect_b32 s19, s21, s19
	s_cselect_b32 s4, s20, s4
	s_add_i32 s20, s19, 1
	s_cmp_ge_u32 s4, s14
	s_cselect_b32 s4, s20, s19
	s_xor_b32 s4, s4, s15
	s_sub_i32 s28, s4, s15
	s_mul_i32 s4, s28, s11
	s_sub_i32 s1, s1, s4
	s_add_i32 s30, s10, s1
	s_cmp_eq_u32 s101, 0
	s_cbranch_scc1 .Lh_el_ok
	s_cmp_gt_u32 s28, 16
	s_cbranch_scc1 .Lh_el_ok
	s_cmp_lt_u32 s28, 3
	s_cbranch_scc1 .Lh_el_ok
	s_cmp_eq_u32 s101, 2
	s_mov_b32 s101, 0
	s_cbranch_scc0 .Lh_el_ok
	s_mov_b64 s[40:41], 0
.Lh_el_ok:
.LBB0_129:
	s_ashr_i32 s31, s30, 31
	v_readlane_b32 s14, v252, 4
	s_lshl_b64 s[10:11], s[30:31], 19
	v_readlane_b32 s1, v252, 14
	v_readlane_b32 s15, v252, 5
	s_add_u32 s20, s1, s10
	v_readlane_b32 s1, v252, 22
	s_load_dwordx4 s[44:47], s[14:15], 0xf0
	s_addc_u32 s21, s1, s11
	s_and_b64 s[10:11], s[40:41], exec
	s_cselect_b32 s1, s21, s43
	s_cselect_b32 s4, s20, s42
	s_ashr_i32 s29, s28, 31
	s_lshl_b64 s[10:11], s[28:29], 19
	s_waitcnt lgkmcnt(0)
	s_add_u32 s36, s44, s10
	s_addc_u32 s37, s45, s11
	s_and_b64 s[10:11], s[40:41], exec
	s_cselect_b32 s10, s37, s13
	s_cselect_b32 s11, s36, s12
	s_add_u32 s42, s42, 0x40080
	s_addc_u32 s43, s43, 0
	s_add_u32 s14, s12, 0x100
	v_mov_b32_e32 v10, 0
	s_addc_u32 s15, s13, 0
	s_mov_b32 s19, -2
	v_mov_b32_e32 v11, v10
	v_mov_b32_e32 v12, v10
	v_mov_b32_e32 v13, v10
	v_mov_b32_e32 v14, v10
	v_mov_b32_e32 v15, v10
	v_mov_b32_e32 v16, v10
	v_mov_b32_e32 v17, v10
	v_mov_b32_e32 v26, v10
	v_mov_b32_e32 v27, v10
	v_mov_b32_e32 v28, v10
	v_mov_b32_e32 v29, v10
	v_mov_b32_e32 v30, v10
	v_mov_b32_e32 v31, v10
	v_mov_b32_e32 v32, v10
	v_mov_b32_e32 v33, v10
	v_mov_b32_e32 v46, v10
	v_mov_b32_e32 v47, v10
	v_mov_b32_e32 v48, v10
	v_mov_b32_e32 v49, v10
	v_mov_b32_e32 v42, v10
	v_mov_b32_e32 v43, v10
	v_mov_b32_e32 v44, v10
	v_mov_b32_e32 v45, v10
	v_mov_b32_e32 v66, v10
	v_mov_b32_e32 v67, v10
	v_mov_b32_e32 v68, v10
	v_mov_b32_e32 v69, v10
	v_mov_b32_e32 v62, v10
	v_mov_b32_e32 v63, v10
	v_mov_b32_e32 v64, v10
	v_mov_b32_e32 v65, v10
	v_mov_b32_e32 v22, v10
	v_mov_b32_e32 v23, v10
	v_mov_b32_e32 v24, v10
	v_mov_b32_e32 v25, v10
	v_mov_b32_e32 v18, v10
	v_mov_b32_e32 v19, v10
	v_mov_b32_e32 v20, v10
	v_mov_b32_e32 v21, v10
	v_mov_b32_e32 v34, v10
	v_mov_b32_e32 v35, v10
	v_mov_b32_e32 v36, v10
	v_mov_b32_e32 v37, v10
	v_mov_b32_e32 v38, v10
	v_mov_b32_e32 v39, v10
	v_mov_b32_e32 v40, v10
	v_mov_b32_e32 v41, v10
	v_mov_b32_e32 v58, v10
	v_mov_b32_e32 v59, v10
	v_mov_b32_e32 v60, v10
	v_mov_b32_e32 v61, v10
	v_mov_b32_e32 v54, v10
	v_mov_b32_e32 v55, v10
	v_mov_b32_e32 v56, v10
	v_mov_b32_e32 v57, v10
	v_mov_b32_e32 v74, v10
	v_mov_b32_e32 v75, v10
	v_mov_b32_e32 v76, v10
	v_mov_b32_e32 v77, v10
	v_mov_b32_e32 v70, v10
	v_mov_b32_e32 v71, v10
	v_mov_b32_e32 v72, v10
	v_mov_b32_e32 v73, v10
	v_mov_b32_e32 v82, v10
	v_mov_b32_e32 v83, v10
	v_mov_b32_e32 v84, v10
	v_mov_b32_e32 v85, v10
	v_mov_b32_e32 v78, v10
	v_mov_b32_e32 v79, v10
	v_mov_b32_e32 v80, v10
	v_mov_b32_e32 v81, v10
	v_mov_b32_e32 v94, v10
	v_mov_b32_e32 v95, v10
	v_mov_b32_e32 v96, v10
	v_mov_b32_e32 v97, v10
	v_mov_b32_e32 v98, v10
	v_mov_b32_e32 v99, v10
	v_mov_b32_e32 v100, v10
	v_mov_b32_e32 v101, v10
	v_mov_b32_e32 v114, v10
	v_mov_b32_e32 v115, v10
	v_mov_b32_e32 v116, v10
	v_mov_b32_e32 v117, v10
	v_mov_b32_e32 v110, v10
	v_mov_b32_e32 v111, v10
	v_mov_b32_e32 v112, v10
	v_mov_b32_e32 v113, v10
	v_mov_b32_e32 v130, v10
	v_mov_b32_e32 v131, v10
	v_mov_b32_e32 v132, v10
	v_mov_b32_e32 v133, v10
	v_mov_b32_e32 v126, v10
	v_mov_b32_e32 v127, v10
	v_mov_b32_e32 v128, v10
	v_mov_b32_e32 v129, v10
	v_mov_b32_e32 v90, v10
	v_mov_b32_e32 v91, v10
	v_mov_b32_e32 v92, v10
	v_mov_b32_e32 v93, v10
	v_mov_b32_e32 v86, v10
	v_mov_b32_e32 v87, v10
	v_mov_b32_e32 v88, v10
	v_mov_b32_e32 v89, v10
	v_mov_b32_e32 v102, v10
	v_mov_b32_e32 v103, v10
	v_mov_b32_e32 v104, v10
	v_mov_b32_e32 v105, v10
	v_mov_b32_e32 v106, v10
	v_mov_b32_e32 v107, v10
	v_mov_b32_e32 v108, v10
	v_mov_b32_e32 v109, v10
	v_mov_b32_e32 v122, v10
	v_mov_b32_e32 v123, v10
	v_mov_b32_e32 v124, v10
	v_mov_b32_e32 v125, v10
	v_mov_b32_e32 v118, v10
	v_mov_b32_e32 v119, v10
	v_mov_b32_e32 v120, v10
	v_mov_b32_e32 v121, v10
	v_mov_b32_e32 v138, v10
	v_mov_b32_e32 v139, v10
	v_mov_b32_e32 v140, v10
	v_mov_b32_e32 v141, v10
	v_mov_b32_e32 v134, v10
	v_mov_b32_e32 v135, v10
	v_mov_b32_e32 v136, v10
	v_mov_b32_e32 v137, v10
; #define PG8_STAGE(bufoff, gbase, voff) do { _Pragma("unroll") for (int _i = 0; _i < 2; ++_i) \
;         __builtin_amdgcn_global_load_lds((const unsigned*)((const char*)(gbase) + (voff)[_i]), (PG8_LAS unsigned*)(lds + (bufoff) + ldsw + _i * 8192), 16, 0, 0); } while (0)
; #define PG8_LDA(dst, b, h) do { _Pragma("unroll") for (int m = 0; m < 4; ++m) _Pragma("unroll") for (int k = 0; k < 2; ++k) dst[m][k] = *(const PG8_LAS bf16x8*)(lds + PG8_SA(b, h) + aoff + m * 2048 + k * 1024); } while (0)
; #define PG8_LDB(dst, b, h) do { _Pragma("unroll") for (int n = 0; n < 2; ++n) _Pragma("unroll") for (int k = 0; k < 2; ++k) dst[n][k] = *(const PG8_LAS bf16x8*)(lds + PG8_SB(b, h) + boff + n * 2048 + k * 1024); } while (0)
; #define PG8_MMA(ai, bj, At, Bt) do { __builtin_amdgcn_s_setprio(1); _Pragma("unroll") for (int m = 0; m < 4; ++m) _Pragma("unroll") for (int n = 0; n < 2; ++n) _Pragma("unroll") for (int k = 0; k < 2; ++k) \
;         acc[ai][bj][m][n] = __builtin_amdgcn_mfma_f32_16x16x32_bf16(Bt[n][k], At[m][k], acc[ai][bj][m][n], 0, 0, 0); __builtin_amdgcn_s_setprio(0); } while (0)
; #define PG8_WAIT_V(n) asm volatile("s_waitcnt vmcnt(" #n ")" ::: "memory")
; #define PG8_WAIT_L(n) asm volatile("s_waitcnt lgkmcnt(" #n ")" ::: "memory")
; #define PG8_BAR __builtin_amdgcn_s_barrier()
; #define PG8_SCHED __builtin_amdgcn_sched_barrier(0)
; template <class Epi, class Sched, bool ALIGN_EPI = false, bool SP2 = false>
; __device__ __forceinline__ void gemm_phase(PG8_LAS unsigned char* lds, const Gemm g, const Sched& S, const Epi& E) {
;     ...
;             PG8_LDB(B0, 0, 0); PG8_LDB(B1, 0, 1); PG8_SCHED; PG8_LDA(At, 0, 0); PG8_STAGE(PG8_SA(1, 1), a1 + hstepA, voffA);
;             PG8_WAIT_V(8); PG8_WAIT_L(0); PG8_BAR; PG8_MMA(0, 0, At, B0); PG8_MMA(0, 1, At, B1); PG8_BAR; PG8_SCHED;
;             PG8_LDA(At, 0, 1); PG8_STAGE(PG8_SB(0, 0), b2, voffB); PG8_STAGE(PG8_SB(0, 1), b2 + hstepB, voffB); PG8_STAGE(PG8_SA(0, 0), a2, voffA);
;             PG8_WAIT_V(8); PG8_WAIT_L(0); PG8_BAR; PG8_MMA(1, 0, At, B0); PG8_MMA(1, 1, At, B1); PG8_BAR; PG8_SCHED;
.LBB0_130:
	s_add_u32 s12, s42, 0xfffc0080
	s_addc_u32 s13, s43, -1
	s_add_i32 s22, 0, 0x10000
	s_cmp_eq_u32 s19, 12
	s_cselect_b32 s45, s1, s13
	s_cselect_b32 s44, s4, s12
	v_add_u32_e32 v8, s22, v185
	s_cselect_b32 s13, s10, s15
	s_cselect_b32 s12, s11, s14
	s_add_i32 s27, 0, 0x14000
	ds_read_b128 v[0:3], v8
	ds_read_b128 v[4:7], v8 offset:1024
	ds_read_b128 v[50:53], v8 offset:2048
	ds_read_b128 v[164:167], v8 offset:3072
	v_add_u32_e32 v8, s27, v185
	ds_read_b128 v[168:171], v8
	ds_read_b128 v[172:175], v8 offset:1024
	ds_read_b128 v[188:191], v8 offset:2048
	ds_read_b128 v[192:195], v8 offset:3072
	v_lshl_add_u64 v[8:9], s[42:43], 0, v[160:161]
	s_add_i32 m0, s54, 0xc000
	ds_read_b128 v[196:199], v186
	ds_read_b128 v[200:203], v186 offset:1024
	ds_read_b128 v[204:207], v186 offset:2048
	ds_read_b128 v[208:211], v186 offset:3072
	ds_read_b128 v[212:215], v186 offset:4096
	ds_read_b128 v[216:219], v186 offset:5120
	ds_read_b128 v[220:223], v186 offset:6144
	ds_read_b128 v[224:227], v186 offset:7168
	global_load_lds_dwordx4 v[8:9], off
	v_lshl_add_u64 v[8:9], s[42:43], 0, v[162:163]
	s_add_i32 m0, s54, 0xe000
	s_nop 0
	global_load_lds_dwordx4 v[8:9], off
	s_waitcnt vmcnt(8)
	s_waitcnt lgkmcnt(0)
	s_barrier
	s_setprio 1
	s_waitcnt lgkmcnt(0)
	s_cmp_eq_u32 s100, 2
	s_cbranch_scc1 .Lhk_0
	v_mfma_f32_16x16x32_bf16 v[134:137], v[0:3], v[196:199], v[134:137]
	v_mfma_f32_16x16x32_bf16 v[138:141], v[50:53], v[196:199], v[138:141]
	v_mfma_f32_16x16x32_bf16 v[118:121], v[0:3], v[204:207], v[118:121]
	v_mfma_f32_16x16x32_bf16 v[122:125], v[50:53], v[204:207], v[122:125]
	v_mfma_f32_16x16x32_bf16 v[106:109], v[0:3], v[212:215], v[106:109]
	v_mfma_f32_16x16x32_bf16 v[102:105], v[50:53], v[212:215], v[102:105]
	v_mfma_f32_16x16x32_bf16 v[86:89], v[0:3], v[220:223], v[86:89]
	v_mfma_f32_16x16x32_bf16 v[90:93], v[50:53], v[220:223], v[90:93]
	v_mfma_f32_16x16x32_bf16 v[134:137], v[4:7], v[200:203], v[134:137]
	v_mfma_f32_16x16x32_bf16 v[138:141], v[164:167], v[200:203], v[138:141]
	v_mfma_f32_16x16x32_bf16 v[118:121], v[4:7], v[208:211], v[118:121]
	v_mfma_f32_16x16x32_bf16 v[122:125], v[164:167], v[208:211], v[122:125]
	v_mfma_f32_16x16x32_bf16 v[106:109], v[4:7], v[216:219], v[106:109]
	v_mfma_f32_16x16x32_bf16 v[102:105], v[164:167], v[216:219], v[102:105]
	v_mfma_f32_16x16x32_bf16 v[86:89], v[4:7], v[224:227], v[86:89]
	v_mfma_f32_16x16x32_bf16 v[90:93], v[164:167], v[224:227], v[90:93]
	s_setprio 0
	s_setprio 1
	v_mfma_f32_16x16x32_bf16 v[126:129], v[168:171], v[196:199], v[126:129]
	v_mfma_f32_16x16x32_bf16 v[130:133], v[188:191], v[196:199], v[130:133]
	v_mfma_f32_16x16x32_bf16 v[110:113], v[168:171], v[204:207], v[110:113]
	v_mfma_f32_16x16x32_bf16 v[114:117], v[188:191], v[204:207], v[114:117]
	v_mfma_f32_16x16x32_bf16 v[98:101], v[168:171], v[212:215], v[98:101]
	v_mfma_f32_16x16x32_bf16 v[94:97], v[188:191], v[212:215], v[94:97]
	v_mfma_f32_16x16x32_bf16 v[78:81], v[168:171], v[220:223], v[78:81]
	v_mfma_f32_16x16x32_bf16 v[82:85], v[188:191], v[220:223], v[82:85]
	v_mfma_f32_16x16x32_bf16 v[126:129], v[172:175], v[200:203], v[126:129]
	v_mfma_f32_16x16x32_bf16 v[130:133], v[192:195], v[200:203], v[130:133]
	v_mfma_f32_16x16x32_bf16 v[110:113], v[172:175], v[208:211], v[110:113]
	v_mfma_f32_16x16x32_bf16 v[114:117], v[192:195], v[208:211], v[114:117]
	v_mfma_f32_16x16x32_bf16 v[98:101], v[172:175], v[216:219], v[98:101]
	v_mfma_f32_16x16x32_bf16 v[94:97], v[192:195], v[216:219], v[94:97]
	v_mfma_f32_16x16x32_bf16 v[78:81], v[172:175], v[224:227], v[78:81]
	v_mfma_f32_16x16x32_bf16 v[82:85], v[192:195], v[224:227], v[82:85]
.Lhk_0:
	s_setprio 0
	s_barrier
	s_add_i32 s22, s22, s33
	v_lshl_add_u64 v[176:177], s[12:13], 0, v[150:151]
	s_mov_b32 m0, s22
	ds_read_b128 v[196:199], v186 offset:16384
	ds_read_b128 v[200:203], v186 offset:17408
	ds_read_b128 v[204:207], v186 offset:18432
	ds_read_b128 v[208:211], v186 offset:19456
	ds_read_b128 v[212:215], v186 offset:20480
	ds_read_b128 v[216:219], v186 offset:21504
	ds_read_b128 v[220:223], v186 offset:22528
	ds_read_b128 v[224:227], v186 offset:23552
	global_load_lds_dwordx4 v[176:177], off
	s_add_i32 m0, s22, 0x2000
	s_add_u32 s22, s12, 0x40000
	v_lshl_add_u64 v[178:179], s[12:13], 0, v[154:155]
	s_addc_u32 s23, s13, 0
	s_add_i32 s27, s27, s33
	global_load_lds_dwordx4 v[178:179], off
	v_lshl_add_u64 v[8:9], s[22:23], 0, v[150:151]
	s_mov_b32 m0, s27
	v_lshl_add_u64 v[228:229], s[44:45], 0, v[148:149]
	global_load_lds_dwordx4 v[8:9], off
	v_lshl_add_u64 v[8:9], s[22:23], 0, v[154:155]
	s_add_i32 m0, s27, 0x2000
	v_lshl_add_u64 v[230:231], s[44:45], 0, v[152:153]
	global_load_lds_dwordx4 v[8:9], off
	s_mov_b32 m0, s54
	s_nop 0
	global_load_lds_dwordx4 v[228:229], off
	s_mov_b32 m0, s55
	s_nop 0
	global_load_lds_dwordx4 v[230:231], off
	s_waitcnt vmcnt(8)
	s_waitcnt lgkmcnt(0)
	s_barrier
	s_setprio 1
	s_waitcnt lgkmcnt(0)
	s_cmp_eq_u32 s100, 1
	s_cbranch_scc1 .Lhk_1
; #define PG8_STAGE(bufoff, gbase, voff) do { _Pragma("unroll") for (int _i = 0; _i < 2; ++_i) \
;         __builtin_amdgcn_global_load_lds((const unsigned*)((const char*)(gbase) + (voff)[_i]), (PG8_LAS unsigned*)(lds + (bufoff) + ldsw + _i * 8192), 16, 0, 0); } while (0)
; #define PG8_LDA(dst, b, h) do { _Pragma("unroll") for (int m = 0; m < 4; ++m) _Pragma("unroll") for (int k = 0; k < 2; ++k) dst[m][k] = *(const PG8_LAS bf16x8*)(lds + PG8_SA(b, h) + aoff + m * 2048 + k * 1024); } while (0)
; #define PG8_LDB(dst, b, h) do { _Pragma("unroll") for (int n = 0; n < 2; ++n) _Pragma("unroll") for (int k = 0; k < 2; ++k) dst[n][k] = *(const PG8_LAS bf16x8*)(lds + PG8_SB(b, h) + boff + n * 2048 + k * 1024); } while (0)
; #define PG8_MMA(ai, bj, At, Bt) do { __builtin_amdgcn_s_setprio(1); _Pragma("unroll") for (int m = 0; m < 4; ++m) _Pragma("unroll") for (int n = 0; n < 2; ++n) _Pragma("unroll") for (int k = 0; k < 2; ++k) \
;         acc[ai][bj][m][n] = __builtin_amdgcn_mfma_f32_16x16x32_bf16(Bt[n][k], At[m][k], acc[ai][bj][m][n], 0, 0, 0); __builtin_amdgcn_s_setprio(0); } while (0)
; #define PG8_WAIT_V(n) asm volatile("s_waitcnt vmcnt(" #n ")" ::: "memory")
; #define PG8_WAIT_L(n) asm volatile("s_waitcnt lgkmcnt(" #n ")" ::: "memory")
; #define PG8_BAR __builtin_amdgcn_s_barrier()
; #define PG8_SCHED __builtin_amdgcn_sched_barrier(0)
; template <class Epi, class Sched, bool ALIGN_EPI = false, bool SP2 = false>
; __device__ __forceinline__ void gemm_phase(PG8_LAS unsigned char* lds, const Gemm g, const Sched& S, const Epi& E) {
;     ...
;             PG8_WAIT_V(8); PG8_WAIT_L(0); PG8_BAR; PG8_MMA(1, 0, At, B0); PG8_MMA(1, 1, At, B1); PG8_BAR; PG8_SCHED;
;             PG8_LDB(B0, 1, 0); PG8_LDB(B1, 1, 1); PG8_SCHED; PG8_LDA(At, 1, 0); PG8_STAGE(PG8_SA(0, 1), a2 + hstepA, voffA);
;             PG8_WAIT_V(8); PG8_WAIT_L(0); PG8_BAR; PG8_MMA(0, 0, At, B0); PG8_MMA(0, 1, At, B1); PG8_BAR; PG8_SCHED;
	v_mfma_f32_16x16x32_bf16 v[70:73], v[0:3], v[196:199], v[70:73]
	v_mfma_f32_16x16x32_bf16 v[74:77], v[50:53], v[196:199], v[74:77]
	v_mfma_f32_16x16x32_bf16 v[54:57], v[0:3], v[204:207], v[54:57]
	v_mfma_f32_16x16x32_bf16 v[58:61], v[50:53], v[204:207], v[58:61]
	v_mfma_f32_16x16x32_bf16 v[38:41], v[0:3], v[212:215], v[38:41]
	v_mfma_f32_16x16x32_bf16 v[34:37], v[50:53], v[212:215], v[34:37]
	v_mfma_f32_16x16x32_bf16 v[0:3], v[0:3], v[220:223], v[18:21]
	v_mfma_f32_16x16x32_bf16 v[70:73], v[4:7], v[200:203], v[70:73]
	v_mfma_f32_16x16x32_bf16 v[74:77], v[164:167], v[200:203], v[74:77]
	v_mfma_f32_16x16x32_bf16 v[54:57], v[4:7], v[208:211], v[54:57]
	v_mfma_f32_16x16x32_bf16 v[58:61], v[164:167], v[208:211], v[58:61]
	v_mfma_f32_16x16x32_bf16 v[38:41], v[4:7], v[216:219], v[38:41]
	v_mfma_f32_16x16x32_bf16 v[34:37], v[164:167], v[216:219], v[34:37]
	v_mfma_f32_16x16x32_bf16 v[0:3], v[4:7], v[224:227], v[0:3]
	v_mfma_f32_16x16x32_bf16 v[4:7], v[50:53], v[220:223], v[22:25]
	v_mfma_f32_16x16x32_bf16 v[4:7], v[164:167], v[224:227], v[4:7]
	s_setprio 0
	s_setprio 1
	v_mfma_f32_16x16x32_bf16 v[18:21], v[168:171], v[196:199], v[62:65]
	v_mfma_f32_16x16x32_bf16 v[50:53], v[172:175], v[200:203], v[18:21]
	v_mfma_f32_16x16x32_bf16 v[18:21], v[188:191], v[196:199], v[66:69]
	v_mfma_f32_16x16x32_bf16 v[66:69], v[192:195], v[200:203], v[18:21]
	v_mfma_f32_16x16x32_bf16 v[18:21], v[168:171], v[204:207], v[42:45]
	v_mfma_f32_16x16x32_bf16 v[42:45], v[172:175], v[208:211], v[18:21]
	v_mfma_f32_16x16x32_bf16 v[18:21], v[188:191], v[204:207], v[46:49]
	v_mfma_f32_16x16x32_bf16 v[46:49], v[192:195], v[208:211], v[18:21]
	v_mfma_f32_16x16x32_bf16 v[18:21], v[168:171], v[212:215], v[30:33]
	v_mfma_f32_16x16x32_bf16 v[30:33], v[172:175], v[216:219], v[18:21]
	v_mfma_f32_16x16x32_bf16 v[18:21], v[188:191], v[212:215], v[26:29]
	v_mfma_f32_16x16x32_bf16 v[14:17], v[168:171], v[220:223], v[14:17]
	v_mfma_f32_16x16x32_bf16 v[8:11], v[188:191], v[220:223], v[10:13]
	v_mfma_f32_16x16x32_bf16 v[26:29], v[192:195], v[216:219], v[18:21]
	v_mfma_f32_16x16x32_bf16 v[14:17], v[172:175], v[224:227], v[14:17]
	v_mfma_f32_16x16x32_bf16 v[8:11], v[192:195], v[224:227], v[8:11]
.Lhk_1:
	s_setprio 0
	s_barrier
	s_add_i32 s27, 0, 0x18000
	v_add_u32_e32 v12, s27, v185
	s_add_i32 s29, 0, 0x1c000
	ds_read_b128 v[18:21], v12
	ds_read_b128 v[22:25], v12 offset:1024
	ds_read_b128 v[62:65], v12 offset:2048
	ds_read_b128 v[164:167], v12 offset:3072
	v_add_u32_e32 v12, s29, v185
	ds_read_b128 v[168:171], v12
	ds_read_b128 v[172:175], v12 offset:1024
	ds_read_b128 v[188:191], v12 offset:2048
	ds_read_b128 v[192:195], v12 offset:3072
	s_add_u32 s22, s44, 0x40000
	s_addc_u32 s23, s45, 0
	s_mov_b32 m0, s16
	v_lshl_add_u64 v[12:13], s[22:23], 0, v[148:149]
	ds_read_b128 v[196:199], v186 offset:32768
	ds_read_b128 v[200:203], v186 offset:33792
	ds_read_b128 v[204:207], v186 offset:34816
	ds_read_b128 v[208:211], v186 offset:35840
	ds_read_b128 v[212:215], v186 offset:36864
	ds_read_b128 v[216:219], v186 offset:37888
	ds_read_b128 v[220:223], v186 offset:38912
	ds_read_b128 v[224:227], v186 offset:39936
	global_load_lds_dwordx4 v[12:13], off
	v_lshl_add_u64 v[12:13], s[22:23], 0, v[152:153]
	s_mov_b32 m0, s17
	s_nop 0
	global_load_lds_dwordx4 v[12:13], off
	s_waitcnt vmcnt(8)
	s_waitcnt lgkmcnt(0)
	s_barrier
	s_setprio 1
	s_waitcnt lgkmcnt(0)
	s_cmp_eq_u32 s100, 2
	s_cbranch_scc1 .Lhk_2
	v_mfma_f32_16x16x32_bf16 v[134:137], v[18:21], v[196:199], v[134:137]
	v_mfma_f32_16x16x32_bf16 v[138:141], v[62:65], v[196:199], v[138:141]
	v_mfma_f32_16x16x32_bf16 v[118:121], v[18:21], v[204:207], v[118:121]
	v_mfma_f32_16x16x32_bf16 v[122:125], v[62:65], v[204:207], v[122:125]
	v_mfma_f32_16x16x32_bf16 v[106:109], v[18:21], v[212:215], v[106:109]
	v_mfma_f32_16x16x32_bf16 v[102:105], v[62:65], v[212:215], v[102:105]
	v_mfma_f32_16x16x32_bf16 v[86:89], v[18:21], v[220:223], v[86:89]
	v_mfma_f32_16x16x32_bf16 v[90:93], v[62:65], v[220:223], v[90:93]
	v_mfma_f32_16x16x32_bf16 v[134:137], v[22:25], v[200:203], v[134:137]
	v_mfma_f32_16x16x32_bf16 v[138:141], v[164:167], v[200:203], v[138:141]
	v_mfma_f32_16x16x32_bf16 v[118:121], v[22:25], v[208:211], v[118:121]
	v_mfma_f32_16x16x32_bf16 v[122:125], v[164:167], v[208:211], v[122:125]
	v_mfma_f32_16x16x32_bf16 v[106:109], v[22:25], v[216:219], v[106:109]
	v_mfma_f32_16x16x32_bf16 v[102:105], v[164:167], v[216:219], v[102:105]
	v_mfma_f32_16x16x32_bf16 v[86:89], v[22:25], v[224:227], v[86:89]
	v_mfma_f32_16x16x32_bf16 v[90:93], v[164:167], v[224:227], v[90:93]
	s_setprio 0
	s_setprio 1
	v_mfma_f32_16x16x32_bf16 v[126:129], v[168:171], v[196:199], v[126:129]
	v_mfma_f32_16x16x32_bf16 v[130:133], v[188:191], v[196:199], v[130:133]
	v_mfma_f32_16x16x32_bf16 v[110:113], v[168:171], v[204:207], v[110:113]
	v_mfma_f32_16x16x32_bf16 v[114:117], v[188:191], v[204:207], v[114:117]
	v_mfma_f32_16x16x32_bf16 v[98:101], v[168:171], v[212:215], v[98:101]
	v_mfma_f32_16x16x32_bf16 v[94:97], v[188:191], v[212:215], v[94:97]
	v_mfma_f32_16x16x32_bf16 v[78:81], v[168:171], v[220:223], v[78:81]
	v_mfma_f32_16x16x32_bf16 v[82:85], v[188:191], v[220:223], v[82:85]
	v_mfma_f32_16x16x32_bf16 v[126:129], v[172:175], v[200:203], v[126:129]
	v_mfma_f32_16x16x32_bf16 v[130:133], v[192:195], v[200:203], v[130:133]
	v_mfma_f32_16x16x32_bf16 v[110:113], v[172:175], v[208:211], v[110:113]
	v_mfma_f32_16x16x32_bf16 v[114:117], v[192:195], v[208:211], v[114:117]
	v_mfma_f32_16x16x32_bf16 v[98:101], v[172:175], v[216:219], v[98:101]
	v_mfma_f32_16x16x32_bf16 v[94:97], v[192:195], v[216:219], v[94:97]
	v_mfma_f32_16x16x32_bf16 v[78:81], v[172:175], v[224:227], v[78:81]
	v_mfma_f32_16x16x32_bf16 v[82:85], v[192:195], v[224:227], v[82:85]
; #define PG8_STAGE(bufoff, gbase, voff) do { _Pragma("unroll") for (int _i = 0; _i < 2; ++_i) \
;         __builtin_amdgcn_global_load_lds((const unsigned*)((const char*)(gbase) + (voff)[_i]), (PG8_LAS unsigned*)(lds + (bufoff) + ldsw + _i * 8192), 16, 0, 0); } while (0)
; #define PG8_LDA(dst, b, h) do { _Pragma("unroll") for (int m = 0; m < 4; ++m) _Pragma("unroll") for (int k = 0; k < 2; ++k) dst[m][k] = *(const PG8_LAS bf16x8*)(lds + PG8_SA(b, h) + aoff + m * 2048 + k * 1024); } while (0)
; #define PG8_MMA(ai, bj, At, Bt) do { __builtin_amdgcn_s_setprio(1); _Pragma("unroll") for (int m = 0; m < 4; ++m) _Pragma("unroll") for (int n = 0; n < 2; ++n) _Pragma("unroll") for (int k = 0; k < 2; ++k) \
;         acc[ai][bj][m][n] = __builtin_amdgcn_mfma_f32_16x16x32_bf16(Bt[n][k], At[m][k], acc[ai][bj][m][n], 0, 0, 0); __builtin_amdgcn_s_setprio(0); } while (0)
; #define PG8_WAIT_V(n) asm volatile("s_waitcnt vmcnt(" #n ")" ::: "memory")
; #define PG8_WAIT_L(n) asm volatile("s_waitcnt lgkmcnt(" #n ")" ::: "memory")
; #define PG8_BAR __builtin_amdgcn_s_barrier()
; #define PG8_SCHED __builtin_amdgcn_sched_barrier(0)
; template <class Epi, class Sched, bool ALIGN_EPI = false, bool SP2 = false>
; __device__ __forceinline__ void gemm_phase(PG8_LAS unsigned char* lds, const Gemm g, const Sched& S, const Epi& E) {
;     ...
;             PG8_WAIT_V(8); PG8_WAIT_L(0); PG8_BAR; PG8_MMA(0, 0, At, B0); PG8_MMA(0, 1, At, B1); PG8_BAR; PG8_SCHED;
;             PG8_LDA(At, 1, 1); PG8_STAGE(PG8_SB(1, 0), b3, voffB); PG8_STAGE(PG8_SB(1, 1), b3 + hstepB, voffB); PG8_STAGE(PG8_SA(1, 0), a3, voffA);
;             PG8_WAIT_V(8); PG8_WAIT_L(0); PG8_BAR; PG8_MMA(1, 0, At, B0); PG8_MMA(1, 1, At, B1); PG8_BAR; PG8_SCHED;
.Lhk_2:
	s_setprio 0
	s_barrier
	s_add_i32 s22, s27, s33
	v_lshl_add_u64 v[12:13], v[176:177], 0, s[6:7]
	s_mov_b32 m0, s22
	ds_read_b128 v[196:199], v186 offset:49152
	ds_read_b128 v[200:203], v186 offset:50176
	ds_read_b128 v[204:207], v186 offset:51200
	ds_read_b128 v[208:211], v186 offset:52224
	ds_read_b128 v[212:215], v186 offset:53248
	ds_read_b128 v[216:219], v186 offset:54272
	ds_read_b128 v[220:223], v186 offset:55296
	ds_read_b128 v[224:227], v186 offset:56320
	global_load_lds_dwordx4 v[12:13], off
	s_add_i32 m0, s22, 0x2000
	s_add_u32 s12, s12, 0x40080
	v_lshl_add_u64 v[12:13], v[178:179], 0, s[6:7]
	s_addc_u32 s13, s13, 0
	s_add_i32 s22, s29, s33
	global_load_lds_dwordx4 v[12:13], off
	v_lshl_add_u64 v[12:13], s[12:13], 0, v[150:151]
	s_mov_b32 m0, s22
	s_nop 0
	global_load_lds_dwordx4 v[12:13], off
	v_lshl_add_u64 v[12:13], s[12:13], 0, v[154:155]
	s_add_i32 m0, s22, 0x2000
	s_nop 0
	global_load_lds_dwordx4 v[12:13], off
	v_lshl_add_u64 v[12:13], v[228:229], 0, s[6:7]
	s_mov_b32 m0, s24
	s_nop 0
	global_load_lds_dwordx4 v[12:13], off
	v_lshl_add_u64 v[12:13], v[230:231], 0, s[6:7]
	s_mov_b32 m0, s25
	s_nop 0
	global_load_lds_dwordx4 v[12:13], off
	s_waitcnt vmcnt(8)
	s_waitcnt lgkmcnt(0)
	s_barrier
	s_setprio 1
	s_waitcnt lgkmcnt(0)
	s_cmp_eq_u32 s100, 1
	s_cbranch_scc1 .Lhk_3
	v_mfma_f32_16x16x32_bf16 v[0:3], v[18:21], v[220:223], v[0:3]
	v_mfma_f32_16x16x32_bf16 v[70:73], v[18:21], v[196:199], v[70:73]
	v_mfma_f32_16x16x32_bf16 v[74:77], v[62:65], v[196:199], v[74:77]
	v_mfma_f32_16x16x32_bf16 v[54:57], v[18:21], v[204:207], v[54:57]
	v_mfma_f32_16x16x32_bf16 v[58:61], v[62:65], v[204:207], v[58:61]
	v_mfma_f32_16x16x32_bf16 v[38:41], v[18:21], v[212:215], v[38:41]
	v_mfma_f32_16x16x32_bf16 v[34:37], v[62:65], v[212:215], v[34:37]
	v_mfma_f32_16x16x32_bf16 v[18:21], v[22:25], v[224:227], v[0:3]
	v_mfma_f32_16x16x32_bf16 v[0:3], v[62:65], v[220:223], v[4:7]
	v_mfma_f32_16x16x32_bf16 v[70:73], v[22:25], v[200:203], v[70:73]
	v_mfma_f32_16x16x32_bf16 v[74:77], v[164:167], v[200:203], v[74:77]
	v_mfma_f32_16x16x32_bf16 v[54:57], v[22:25], v[208:211], v[54:57]
	v_mfma_f32_16x16x32_bf16 v[58:61], v[164:167], v[208:211], v[58:61]
	v_mfma_f32_16x16x32_bf16 v[38:41], v[22:25], v[216:219], v[38:41]
	v_mfma_f32_16x16x32_bf16 v[34:37], v[164:167], v[216:219], v[34:37]
	v_mfma_f32_16x16x32_bf16 v[22:25], v[164:167], v[224:227], v[0:3]
	s_setprio 0
	s_setprio 1
	v_mfma_f32_16x16x32_bf16 v[0:3], v[168:171], v[196:199], v[50:53]
	v_mfma_f32_16x16x32_bf16 v[62:65], v[172:175], v[200:203], v[0:3]
	v_mfma_f32_16x16x32_bf16 v[0:3], v[188:191], v[196:199], v[66:69]
	v_mfma_f32_16x16x32_bf16 v[66:69], v[192:195], v[200:203], v[0:3]
	v_mfma_f32_16x16x32_bf16 v[0:3], v[168:171], v[204:207], v[42:45]
	v_mfma_f32_16x16x32_bf16 v[42:45], v[172:175], v[208:211], v[0:3]
	v_mfma_f32_16x16x32_bf16 v[0:3], v[188:191], v[204:207], v[46:49]
	v_mfma_f32_16x16x32_bf16 v[46:49], v[192:195], v[208:211], v[0:3]
	v_mfma_f32_16x16x32_bf16 v[0:3], v[168:171], v[212:215], v[30:33]
	v_mfma_f32_16x16x32_bf16 v[30:33], v[172:175], v[216:219], v[0:3]
	v_mfma_f32_16x16x32_bf16 v[0:3], v[188:191], v[212:215], v[26:29]
	v_mfma_f32_16x16x32_bf16 v[26:29], v[192:195], v[216:219], v[0:3]
	v_mfma_f32_16x16x32_bf16 v[0:3], v[168:171], v[220:223], v[14:17]
	v_mfma_f32_16x16x32_bf16 v[14:17], v[172:175], v[224:227], v[0:3]
	v_mfma_f32_16x16x32_bf16 v[0:3], v[188:191], v[220:223], v[8:11]
	v_mfma_f32_16x16x32_bf16 v[10:13], v[192:195], v[224:227], v[0:3]
.Lhk_3:
	s_setprio 0
	s_barrier
	s_add_i32 s19, s19, 2
	s_add_u32 s42, s42, 0x100
	s_addc_u32 s43, s43, 0
	s_add_u32 s14, s14, 0x100
	s_addc_u32 s15, s15, 0
	s_cmp_gt_u32 s19, 13
	s_cbranch_scc0 .LBB0_130
	v_readlane_b32 s10, v253, 25
	v_readlane_b32 s11, v253, 26
	s_and_b64 vcc, exec, s[10:11]
	s_cbranch_vccz .LBB0_133
	s_barrier

; __device__ __forceinline__ unsigned cvt_pk_bf16(float lo, float hi) { unsigned r; asm volatile("v_cvt_pk_bf16_f32 %0, %1, %2" : "=v"(r) : "v"(lo), "v"(hi)); return r; }
;     __device__ __forceinline__ void operator()(const f32x4 (&acc)[2][2][4][2], const Unit& u, int wr, int wc, int fr, int fq) const {
;     ...
; #pragma unroll
;         for (int ai = 0; ai < 2; ++ai)
; #pragma unroll
;             for (int m = 0; m < 4; ++m) {
;                 const int row = u.pm * BM + ai * HALF + wr * 64 + m * 16 + fr;
;                 const bool isP = row < MP, isS = (row >= MP) && (row < MT);
;                 const int b = isP ? (row >> 12) : (row - MP);
;                 const int t = row & 4095;
;                 float cosv[8], sinv[8];
;                 if (do_rope) {
;                     const f32x4* cs = (const f32x4*)(rope + (size_t)(isP ? t : 4096) * 16);
; #pragma unroll
;                     for (int q = 0; q < 4; ++q) { const f32x4 c = cs[q]; cosv[2 * q] = c[0]; sinv[2 * q] = c[1]; cosv[2 * q + 1] = c[2]; sinv[2 * q + 1] = c[3]; }
;                 }
; #pragma unroll
;                 for (int bj = 0; bj < 2; ++bj) {
;                     f32x4 v0 = acc[ai][bj][m][0], v1 = acc[ai][bj][m][1];
;                     const int cit = bj * HALF + wc * 32 + fq * 8;
;                     if (do_rope) {
; #pragma unroll
;                         for (int j = 0; j < 4; ++j) {
;                             const float p0 = __shfl_xor(v0[j], 16), p1 = __shfl_xor(v1[j], 16);
;                             const float r0 = v0[j] * cosv[j] + sgn * p0 * sinv[j], r1 = v1[j] * cosv[4 + j] + sgn * p1 * sinv[4 + j];
;                             v0[j] = fq < 2 ? r0 : v0[j]; v1[j] = fq < 2 ? r1 : v1[j];
;                         }
;                     }
;                     if (pn < 3) { v0 = v0 * QSCALE; v1 = v1 * QSCALE; }
;                     u32x4 w; w.x = cvt_pk_bf16(v0[0], v0[1]); w.y = cvt_pk_bf16(v0[2], v0[3]); w.z = cvt_pk_bf16(v1[0], v1[1]); w.w = cvt_pk_bf16(v1[2], v1[3]);
;                     *(u32x4*)(Z + (size_t)row * NZ + pn * BM + cit) = w;
.Lz_lean:
	s_lshl_b32 s98, s48, 9
	v_lshlrev_b32_e32 v164, 1, v158
	v_add_u32_e32 v164, s98, v164
	v_mov_b32_e32 v165, 0
	s_movk_i32 s99, 0x4200
	v_mad_u64_u32 v[166:167], vcc, v187, s99, v[164:165]
	v_lshl_add_u64 v[166:167], s[2:3], 0, v[166:167]
	s_cmp_eq_u32 s100, 2
	s_cbranch_scc1 .Lz_lean_hi
	v_cvt_pk_bf16_f32 v196, v134, v135
	v_cvt_pk_bf16_f32 v197, v136, v137
	v_cvt_pk_bf16_f32 v198, v138, v139
	v_cvt_pk_bf16_f32 v199, v140, v141
	global_store_dwordx4 v[166:167], v[196:199], off
	v_cvt_pk_bf16_f32 v200, v126, v127
	v_cvt_pk_bf16_f32 v201, v128, v129
	v_cvt_pk_bf16_f32 v202, v130, v131
	v_cvt_pk_bf16_f32 v203, v132, v133
	global_store_dwordx4 v[166:167], v[200:203], off offset:256
	s_mov_b32 vcc_lo, 0x42000
	s_mov_b32 vcc_hi, 0
	v_lshl_add_u64 v[168:169], v[166:167], 0, vcc
	v_cvt_pk_bf16_f32 v204, v118, v119
	v_cvt_pk_bf16_f32 v205, v120, v121
	v_cvt_pk_bf16_f32 v206, v122, v123
	v_cvt_pk_bf16_f32 v207, v124, v125
	global_store_dwordx4 v[168:169], v[204:207], off
	v_cvt_pk_bf16_f32 v208, v110, v111
	v_cvt_pk_bf16_f32 v209, v112, v113
	v_cvt_pk_bf16_f32 v210, v114, v115
	v_cvt_pk_bf16_f32 v211, v116, v117
	global_store_dwordx4 v[168:169], v[208:211], off offset:256
	s_mov_b32 vcc_lo, 0x84000
	s_mov_b32 vcc_hi, 0
	v_lshl_add_u64 v[168:169], v[166:167], 0, vcc
	v_cvt_pk_bf16_f32 v196, v106, v107
	v_cvt_pk_bf16_f32 v197, v108, v109
	v_cvt_pk_bf16_f32 v198, v102, v103
	v_cvt_pk_bf16_f32 v199, v104, v105
	global_store_dwordx4 v[168:169], v[196:199], off
	v_cvt_pk_bf16_f32 v200, v98, v99
	v_cvt_pk_bf16_f32 v201, v100, v101
	v_cvt_pk_bf16_f32 v202, v94, v95
	v_cvt_pk_bf16_f32 v203, v96, v97
	global_store_dwordx4 v[168:169], v[200:203], off offset:256
	s_mov_b32 vcc_lo, 0xc6000
	s_mov_b32 vcc_hi, 0
	v_lshl_add_u64 v[168:169], v[166:167], 0, vcc
	v_cvt_pk_bf16_f32 v204, v86, v87
	v_cvt_pk_bf16_f32 v205, v88, v89
	v_cvt_pk_bf16_f32 v206, v90, v91
	v_cvt_pk_bf16_f32 v207, v92, v93
	global_store_dwordx4 v[168:169], v[204:207], off
	v_cvt_pk_bf16_f32 v208, v78, v79
	v_cvt_pk_bf16_f32 v209, v80, v81
	v_cvt_pk_bf16_f32 v210, v82, v83
	v_cvt_pk_bf16_f32 v211, v84, v85
	global_store_dwordx4 v[168:169], v[208:211], off offset:256
	s_cmp_eq_u32 s100, 1
	s_cbranch_scc1 .LBB0_297
.Lz_lean_hi:
	s_mov_b32 vcc_lo, 0x210000
	s_mov_b32 vcc_hi, 0
	v_lshl_add_u64 v[168:169], v[166:167], 0, vcc
	v_cvt_pk_bf16_f32 v196, v70, v71
	v_cvt_pk_bf16_f32 v197, v72, v73
	v_cvt_pk_bf16_f32 v198, v74, v75
	v_cvt_pk_bf16_f32 v199, v76, v77
	global_store_dwordx4 v[168:169], v[196:199], off
	v_cvt_pk_bf16_f32 v200, v62, v63
	v_cvt_pk_bf16_f32 v201, v64, v65
	v_cvt_pk_bf16_f32 v202, v66, v67
	v_cvt_pk_bf16_f32 v203, v68, v69
	global_store_dwordx4 v[168:169], v[200:203], off offset:256
	s_mov_b32 vcc_lo, 0x252000
	s_mov_b32 vcc_hi, 0
	v_lshl_add_u64 v[168:169], v[166:167], 0, vcc
	v_cvt_pk_bf16_f32 v204, v54, v55
	v_cvt_pk_bf16_f32 v205, v56, v57
	v_cvt_pk_bf16_f32 v206, v58, v59
	v_cvt_pk_bf16_f32 v207, v60, v61
	global_store_dwordx4 v[168:169], v[204:207], off
	v_cvt_pk_bf16_f32 v208, v42, v43
	v_cvt_pk_bf16_f32 v209, v44, v45
	v_cvt_pk_bf16_f32 v210, v46, v47
	v_cvt_pk_bf16_f32 v211, v48, v49
	global_store_dwordx4 v[168:169], v[208:211], off offset:256
	s_mov_b32 vcc_lo, 0x294000
	s_mov_b32 vcc_hi, 0
	v_lshl_add_u64 v[168:169], v[166:167], 0, vcc
	v_cvt_pk_bf16_f32 v196, v38, v39
	v_cvt_pk_bf16_f32 v197, v40, v41
	v_cvt_pk_bf16_f32 v198, v34, v35
	v_cvt_pk_bf16_f32 v199, v36, v37
	global_store_dwordx4 v[168:169], v[196:199], off
	v_cvt_pk_bf16_f32 v200, v30, v31
	v_cvt_pk_bf16_f32 v201, v32, v33
	v_cvt_pk_bf16_f32 v202, v26, v27
	v_cvt_pk_bf16_f32 v203, v28, v29
	global_store_dwordx4 v[168:169], v[200:203], off offset:256
	s_mov_b32 vcc_lo, 0x2d6000
	s_mov_b32 vcc_hi, 0
	v_lshl_add_u64 v[168:169], v[166:167], 0, vcc
	v_cvt_pk_bf16_f32 v204, v18, v19
	v_cvt_pk_bf16_f32 v205, v20, v21
	v_cvt_pk_bf16_f32 v206, v22, v23
	v_cvt_pk_bf16_f32 v207, v24, v25
	global_store_dwordx4 v[168:169], v[204:207], off
	v_cvt_pk_bf16_f32 v208, v14, v15
	v_cvt_pk_bf16_f32 v209, v16, v17
	v_cvt_pk_bf16_f32 v210, v10, v11
	v_cvt_pk_bf16_f32 v211, v12, v13
	global_store_dwordx4 v[168:169], v[208:211], off offset:256
	s_branch .LBB0_297

; __device__ __forceinline__ unsigned cvt_pk_bf16(float lo, float hi) { unsigned r; asm volatile("v_cvt_pk_bf16_f32 %0, %1, %2" : "=v"(r) : "v"(lo), "v"(hi)); return r; }
;     __device__ __forceinline__ void operator()(const f32x4 (&acc)[2][2][4][2], const Unit& u, int wr, int wc, int fr, int fq) const {
;     ...
; #pragma unroll
;         for (int ai = 0; ai < 2; ++ai)
; #pragma unroll
;             for (int m = 0; m < 4; ++m) {
;                 const int row = u.pm * BM + ai * HALF + wr * 64 + m * 16 + fr;
;                 const bool isP = row < MP, isS = (row >= MP) && (row < MT);
;                 const int b = isP ? (row >> 12) : (row - MP);
;                 const int t = row & 4095;
;                 float cosv[8], sinv[8];
;                 if (do_rope) {
;                     const f32x4* cs = (const f32x4*)(rope + (size_t)(isP ? t : 4096) * 16);
; #pragma unroll
;                     for (int q = 0; q < 4; ++q) { const f32x4 c = cs[q]; cosv[2 * q] = c[0]; sinv[2 * q] = c[1]; cosv[2 * q + 1] = c[2]; sinv[2 * q + 1] = c[3]; }
;                 }
; #pragma unroll
;                 for (int bj = 0; bj < 2; ++bj) {
;                     f32x4 v0 = acc[ai][bj][m][0], v1 = acc[ai][bj][m][1];
;                     const int cit = bj * HALF + wc * 32 + fq * 8;
;                     if (do_rope) {
; #pragma unroll
;                         for (int j = 0; j < 4; ++j) {
;                             const float p0 = __shfl_xor(v0[j], 16), p1 = __shfl_xor(v1[j], 16);
;                             const float r0 = v0[j] * cosv[j] + sgn * p0 * sinv[j], r1 = v1[j] * cosv[4 + j] + sgn * p1 * sinv[4 + j];
;                             v0[j] = fq < 2 ? r0 : v0[j]; v1[j] = fq < 2 ? r1 : v1[j];
;                         }
;                     }
;                     if (pn < 3) { v0 = v0 * QSCALE; v1 = v1 * QSCALE; }
;                     u32x4 w; w.x = cvt_pk_bf16(v0[0], v0[1]); w.y = cvt_pk_bf16(v0[2], v0[3]); w.z = cvt_pk_bf16(v1[0], v1[1]); w.w = cvt_pk_bf16(v1[2], v1[3]);
;                     *(u32x4*)(Z + (size_t)row * NZ + pn * BM + cit) = w;
.Lz_nokv:
	s_cmp_lg_u32 s10, 0
	s_cbranch_scc1 .Lz_ropewave
	s_cmp_eq_u32 s100, 2
	s_cbranch_scc1 .Lz_pl_hi
	s_cmp_lt_u32 s48, 3
	s_cbranch_scc0 .Lz_pl_noqs0
	v_mul_f32_e32 v134, s8, v134
	v_mul_f32_e32 v135, s8, v135
	v_mul_f32_e32 v136, s8, v136
	v_mul_f32_e32 v137, s8, v137
	v_mul_f32_e32 v138, s8, v138
	v_mul_f32_e32 v139, s8, v139
	v_mul_f32_e32 v140, s8, v140
	v_mul_f32_e32 v141, s8, v141
	v_mul_f32_e32 v126, s8, v126
	v_mul_f32_e32 v127, s8, v127
	v_mul_f32_e32 v128, s8, v128
	v_mul_f32_e32 v129, s8, v129
	v_mul_f32_e32 v130, s8, v130
	v_mul_f32_e32 v131, s8, v131
	v_mul_f32_e32 v132, s8, v132
	v_mul_f32_e32 v133, s8, v133

; __device__ __forceinline__ unsigned cvt_pk_bf16(float lo, float hi) { unsigned r; asm volatile("v_cvt_pk_bf16_f32 %0, %1, %2" : "=v"(r) : "v"(lo), "v"(hi)); return r; }
;     __device__ __forceinline__ void operator()(const f32x4 (&acc)[2][2][4][2], const Unit& u, int wr, int wc, int fr, int fq) const {
;     ...
; #pragma unroll
;         for (int ai = 0; ai < 2; ++ai)
; #pragma unroll
;             for (int m = 0; m < 4; ++m) {
;                 const int row = u.pm * BM + ai * HALF + wr * 64 + m * 16 + fr;
;                 const bool isP = row < MP, isS = (row >= MP) && (row < MT);
;                 const int b = isP ? (row >> 12) : (row - MP);
;                 const int t = row & 4095;
;                 float cosv[8], sinv[8];
;                 if (do_rope) {
;                     const f32x4* cs = (const f32x4*)(rope + (size_t)(isP ? t : 4096) * 16);
; #pragma unroll
;                     for (int q = 0; q < 4; ++q) { const f32x4 c = cs[q]; cosv[2 * q] = c[0]; sinv[2 * q] = c[1]; cosv[2 * q + 1] = c[2]; sinv[2 * q + 1] = c[3]; }
;                 }
; #pragma unroll
;                 for (int bj = 0; bj < 2; ++bj) {
;                     f32x4 v0 = acc[ai][bj][m][0], v1 = acc[ai][bj][m][1];
;                     const int cit = bj * HALF + wc * 32 + fq * 8;
;                     if (do_rope) {
; #pragma unroll
;                         for (int j = 0; j < 4; ++j) {
;                             const float p0 = __shfl_xor(v0[j], 16), p1 = __shfl_xor(v1[j], 16);
;                             const float r0 = v0[j] * cosv[j] + sgn * p0 * sinv[j], r1 = v1[j] * cosv[4 + j] + sgn * p1 * sinv[4 + j];
;                             v0[j] = fq < 2 ? r0 : v0[j]; v1[j] = fq < 2 ? r1 : v1[j];
;                         }
;                     }
;                     if (pn < 3) { v0 = v0 * QSCALE; v1 = v1 * QSCALE; }
;                     u32x4 w; w.x = cvt_pk_bf16(v0[0], v0[1]); w.y = cvt_pk_bf16(v0[2], v0[3]); w.z = cvt_pk_bf16(v1[0], v1[1]); w.w = cvt_pk_bf16(v1[2], v1[3]);
;                     *(u32x4*)(Z + (size_t)row * NZ + pn * BM + cit) = w;
.Lz_pl_nokv3:
	s_cmp_eq_u32 s100, 1
	s_cbranch_scc1 .LBB0_297

;     __device__ __forceinline__ void operator()(const f32x4 (&acc)[2][2][4][2], const Unit& u, int wr, int wc, int fr, int fq) const {
;     ...
;                 if (do_rope) {
;                     const f32x4* cs = (const f32x4*)(rope + (size_t)(isP ? t : 4096) * 16);
; #pragma unroll
;                     for (int q = 0; q < 4; ++q) { const f32x4 c = cs[q]; cosv[2 * q] = c[0]; sinv[2 * q] = c[1]; cosv[2 * q + 1] = c[2]; sinv[2 * q + 1] = c[3]; }
;                 }
; #pragma unroll
;                 for (int bj = 0; bj < 2; ++bj) {
;                     f32x4 v0 = acc[ai][bj][m][0], v1 = acc[ai][bj][m][1];
;                     const int cit = bj * HALF + wc * 32 + fq * 8;
;                     if (do_rope) {
; #pragma unroll
;                         for (int j = 0; j < 4; ++j) {
;                             const float p0 = __shfl_xor(v0[j], 16), p1 = __shfl_xor(v1[j], 16);
;                             const float r0 = v0[j] * cosv[j] + sgn * p0 * sinv[j], r1 = v1[j] * cosv[4 + j] + sgn * p1 * sinv[4 + j];
;                             v0[j] = fq < 2 ? r0 : v0[j]; v1[j] = fq < 2 ? r1 : v1[j];
;                         }
;                     }
.Lz_rw_p:
	v_and_b32_e32 v8, 32, v183
	v_cmp_eq_u32_e32 vcc, 0, v8
	s_nop 1
	v_cndmask_b32_e32 v170, 0, v170, vcc
	v_cndmask_b32_e32 v171, 0, v171, vcc
	s_cmp_eq_u32 s100, 1
	s_cbranch_scc1 .Lz_rw_lo
	s_cmp_eq_u32 s100, 2
	s_cbranch_scc1 .Lz_rw_hi
	global_load_dwordx4 v[196:199], v170, s[34:35]
	global_load_dwordx4 v[200:203], v170, s[34:35] offset:16
	global_load_dwordx4 v[204:207], v170, s[34:35] offset:32
	global_load_dwordx4 v[208:211], v170, s[34:35] offset:48
	s_movk_i32 s98, 0x10
	v_mad_u32_u24 v9, v171, s98, v170
	global_load_dwordx4 v[212:215], v9, s[34:35]
	global_load_dwordx4 v[216:219], v9, s[34:35] offset:16
	global_load_dwordx4 v[220:223], v9, s[34:35] offset:32
	global_load_dwordx4 v[224:227], v9, s[34:35] offset:48
	s_movk_i32 s98, 0x20
	v_mad_u32_u24 v8, v171, s98, v170
	global_load_dwordx4 v[0:3], v8, s[34:35]
	global_load_dwordx4 v[4:7], v8, s[34:35] offset:16
	global_load_dwordx4 v[176:179], v8, s[34:35] offset:32
	global_load_dwordx4 v[172:175], v8, s[34:35] offset:48
	s_waitcnt vmcnt(8)
	v_permlane16_swap_b32_e32 v134, v126
	v_permlane16_swap_b32_e32 v135, v127
	v_permlane16_swap_b32_e32 v136, v128
	v_permlane16_swap_b32_e32 v137, v129
	v_permlane16_swap_b32_e32 v138, v130
	v_permlane16_swap_b32_e32 v139, v131
	v_permlane16_swap_b32_e32 v140, v132
	v_permlane16_swap_b32_e32 v141, v133
	v_mul_f32_e32 v188, v126, v197
	v_mul_f32_e32 v197, v134, v197
	v_mul_f32_e32 v189, v127, v199
	v_mul_f32_e32 v199, v135, v199
	v_mul_f32_e32 v190, v128, v201
	v_mul_f32_e32 v201, v136, v201
	v_mul_f32_e32 v191, v129, v203
	v_mul_f32_e32 v203, v137, v203
	v_mul_f32_e32 v192, v130, v205
	v_mul_f32_e32 v205, v138, v205
	v_mul_f32_e32 v193, v131, v207
	v_mul_f32_e32 v207, v139, v207
	v_mul_f32_e32 v194, v132, v209
	v_mul_f32_e32 v209, v140, v209
	v_mul_f32_e32 v195, v133, v211
	v_mul_f32_e32 v211, v141, v211
	v_fma_f32 v134, v134, v196, -v188
	v_fma_f32 v126, v126, v196, v197
	v_fma_f32 v135, v135, v198, -v189
	v_fma_f32 v127, v127, v198, v199
	v_fma_f32 v136, v136, v200, -v190
	v_fma_f32 v128, v128, v200, v201
	v_fma_f32 v137, v137, v202, -v191
	v_fma_f32 v129, v129, v202, v203
	v_fma_f32 v138, v138, v204, -v192
	v_fma_f32 v130, v130, v204, v205
	v_fma_f32 v139, v139, v206, -v193
	v_fma_f32 v131, v131, v206, v207
	v_fma_f32 v140, v140, v208, -v194
	v_fma_f32 v132, v132, v208, v209
	v_fma_f32 v141, v141, v210, -v195
	v_fma_f32 v133, v133, v210, v211
	v_permlane16_swap_b32_e32 v134, v126
	v_permlane16_swap_b32_e32 v135, v127
	v_permlane16_swap_b32_e32 v136, v128
	v_permlane16_swap_b32_e32 v137, v129
	v_permlane16_swap_b32_e32 v138, v130
	v_permlane16_swap_b32_e32 v139, v131
	v_permlane16_swap_b32_e32 v140, v132
	v_permlane16_swap_b32_e32 v141, v133
	s_cmp_lt_u32 s48, 3
	s_cbranch_scc0 .Lz_rw_noqs0
	v_mul_f32_e32 v134, s8, v134
	v_mul_f32_e32 v135, s8, v135
	v_mul_f32_e32 v136, s8, v136
	v_mul_f32_e32 v137, s8, v137
	v_mul_f32_e32 v138, s8, v138
	v_mul_f32_e32 v139, s8, v139
	v_mul_f32_e32 v140, s8, v140
	v_mul_f32_e32 v141, s8, v141
	v_mul_f32_e32 v126, s8, v126
	v_mul_f32_e32 v127, s8, v127
	v_mul_f32_e32 v128, s8, v128
	v_mul_f32_e32 v129, s8, v129
	v_mul_f32_e32 v130, s8, v130
	v_mul_f32_e32 v131, s8, v131
	v_mul_f32_e32 v132, s8, v132
	v_mul_f32_e32 v133, s8, v133

;     __device__ __forceinline__ void operator()(const f32x4 (&acc)[2][2][4][2], const Unit& u, int wr, int wc, int fr, int fq) const {
;     ...
;                 const int row = u.pm * BM + ai * HALF + wr * 64 + m * 16 + fr;
;                 const bool isP = row < MP, isS = (row >= MP) && (row < MT);
;                 const int b = isP ? (row >> 12) : (row - MP);
;                 const int t = row & 4095;
;                 float cosv[8], sinv[8];
;                 if (do_rope) {
;                     const f32x4* cs = (const f32x4*)(rope + (size_t)(isP ? t : 4096) * 16);
; #pragma unroll
;                     for (int q = 0; q < 4; ++q) { const f32x4 c = cs[q]; cosv[2 * q] = c[0]; sinv[2 * q] = c[1]; cosv[2 * q + 1] = c[2]; sinv[2 * q + 1] = c[3]; }
;                 }
; #pragma unroll
;                 for (int bj = 0; bj < 2; ++bj) {
;                     f32x4 v0 = acc[ai][bj][m][0], v1 = acc[ai][bj][m][1];
;                     const int cit = bj * HALF + wc * 32 + fq * 8;
;                     if (do_rope) {
; #pragma unroll
;                         for (int j = 0; j < 4; ++j) {
;                             const float p0 = __shfl_xor(v0[j], 16), p1 = __shfl_xor(v1[j], 16);
;                             const float r0 = v0[j] * cosv[j] + sgn * p0 * sinv[j], r1 = v1[j] * cosv[4 + j] + sgn * p1 * sinv[4 + j];
;                             v0[j] = fq < 2 ? r0 : v0[j]; v1[j] = fq < 2 ? r1 : v1[j];
;                         }
;                     }
;                     if (pn < 3) { v0 = v0 * QSCALE; v1 = v1 * QSCALE; }
.Lz_rw_lo:
	global_load_dwordx4 v[196:199], v170, s[34:35]
	global_load_dwordx4 v[200:203], v170, s[34:35] offset:16
	global_load_dwordx4 v[204:207], v170, s[34:35] offset:32
	global_load_dwordx4 v[208:211], v170, s[34:35] offset:48
	s_movk_i32 s98, 0x10
	v_mad_u32_u24 v9, v171, s98, v170
	global_load_dwordx4 v[212:215], v9, s[34:35]
	global_load_dwordx4 v[216:219], v9, s[34:35] offset:16
	global_load_dwordx4 v[220:223], v9, s[34:35] offset:32
	global_load_dwordx4 v[224:227], v9, s[34:35] offset:48
	s_movk_i32 s98, 0x20
	v_mad_u32_u24 v8, v171, s98, v170
	global_load_dwordx4 v[0:3], v8, s[34:35]
	global_load_dwordx4 v[4:7], v8, s[34:35] offset:16
	global_load_dwordx4 v[176:179], v8, s[34:35] offset:32
	global_load_dwordx4 v[172:175], v8, s[34:35] offset:48
	s_waitcnt vmcnt(8)
	v_permlane16_swap_b32_e32 v134, v126
	v_permlane16_swap_b32_e32 v135, v127
	v_permlane16_swap_b32_e32 v136, v128
	v_permlane16_swap_b32_e32 v137, v129
	v_permlane16_swap_b32_e32 v138, v130
	v_permlane16_swap_b32_e32 v139, v131
	v_permlane16_swap_b32_e32 v140, v132
	v_permlane16_swap_b32_e32 v141, v133
	v_mul_f32_e32 v188, v126, v197
	v_mul_f32_e32 v197, v134, v197
	v_mul_f32_e32 v189, v127, v199
	v_mul_f32_e32 v199, v135, v199
	v_mul_f32_e32 v190, v128, v201
	v_mul_f32_e32 v201, v136, v201
	v_mul_f32_e32 v191, v129, v203
	v_mul_f32_e32 v203, v137, v203
	v_mul_f32_e32 v192, v130, v205
	v_mul_f32_e32 v205, v138, v205
	v_mul_f32_e32 v193, v131, v207
	v_mul_f32_e32 v207, v139, v207
	v_mul_f32_e32 v194, v132, v209
	v_mul_f32_e32 v209, v140, v209
	v_mul_f32_e32 v195, v133, v211
	v_mul_f32_e32 v211, v141, v211
	v_fma_f32 v134, v134, v196, -v188
	v_fma_f32 v126, v126, v196, v197
	v_fma_f32 v135, v135, v198, -v189
	v_fma_f32 v127, v127, v198, v199
	v_fma_f32 v136, v136, v200, -v190
	v_fma_f32 v128, v128, v200, v201
	v_fma_f32 v137, v137, v202, -v191
	v_fma_f32 v129, v129, v202, v203
	v_fma_f32 v138, v138, v204, -v192
	v_fma_f32 v130, v130, v204, v205
	v_fma_f32 v139, v139, v206, -v193
	v_fma_f32 v131, v131, v206, v207
	v_fma_f32 v140, v140, v208, -v194
	v_fma_f32 v132, v132, v208, v209
	v_fma_f32 v141, v141, v210, -v195
	v_fma_f32 v133, v133, v210, v211
	v_permlane16_swap_b32_e32 v134, v126
	v_permlane16_swap_b32_e32 v135, v127
	v_permlane16_swap_b32_e32 v136, v128
	v_permlane16_swap_b32_e32 v137, v129
	v_permlane16_swap_b32_e32 v138, v130
	v_permlane16_swap_b32_e32 v139, v131
	v_permlane16_swap_b32_e32 v140, v132
	v_permlane16_swap_b32_e32 v141, v133
	s_cmp_lt_u32 s48, 3
	s_cbranch_scc0 .Lz_rl_noqs0
	v_mul_f32_e32 v134, s8, v134
	v_mul_f32_e32 v135, s8, v135
	v_mul_f32_e32 v136, s8, v136
	v_mul_f32_e32 v137, s8, v137
	v_mul_f32_e32 v138, s8, v138
	v_mul_f32_e32 v139, s8, v139
	v_mul_f32_e32 v140, s8, v140
	v_mul_f32_e32 v141, s8, v141
	v_mul_f32_e32 v126, s8, v126
	v_mul_f32_e32 v127, s8, v127
	v_mul_f32_e32 v128, s8, v128
	v_mul_f32_e32 v129, s8, v129
	v_mul_f32_e32 v130, s8, v130
	v_mul_f32_e32 v131, s8, v131
	v_mul_f32_e32 v132, s8, v132
	v_mul_f32_e32 v133, s8, v133

;     __device__ __forceinline__ void operator()(const f32x4 (&acc)[2][2][4][2], const Unit& u, int wr, int wc, int fr, int fq) const {
;     ...
;                 const int row = u.pm * BM + ai * HALF + wr * 64 + m * 16 + fr;
;                 const bool isP = row < MP, isS = (row >= MP) && (row < MT);
;                 const int b = isP ? (row >> 12) : (row - MP);
;                 const int t = row & 4095;
;                 float cosv[8], sinv[8];
;                 if (do_rope) {
;                     const f32x4* cs = (const f32x4*)(rope + (size_t)(isP ? t : 4096) * 16);
; #pragma unroll
;                     for (int q = 0; q < 4; ++q) { const f32x4 c = cs[q]; cosv[2 * q] = c[0]; sinv[2 * q] = c[1]; cosv[2 * q + 1] = c[2]; sinv[2 * q + 1] = c[3]; }
;                 }
; #pragma unroll
;                 for (int bj = 0; bj < 2; ++bj) {
;                     f32x4 v0 = acc[ai][bj][m][0], v1 = acc[ai][bj][m][1];
;                     const int cit = bj * HALF + wc * 32 + fq * 8;
;                     if (do_rope) {
; #pragma unroll
;                         for (int j = 0; j < 4; ++j) {
;                             const float p0 = __shfl_xor(v0[j], 16), p1 = __shfl_xor(v1[j], 16);
;                             const float r0 = v0[j] * cosv[j] + sgn * p0 * sinv[j], r1 = v1[j] * cosv[4 + j] + sgn * p1 * sinv[4 + j];
;                             v0[j] = fq < 2 ? r0 : v0[j]; v1[j] = fq < 2 ? r1 : v1[j];
;                         }
;                     }
;                     if (pn < 3) { v0 = v0 * QSCALE; v1 = v1 * QSCALE; }
.Lz_rl_nokv1:
	s_mov_b32 vcc_lo, 0x84000
	s_mov_b32 vcc_hi, 0
	v_lshl_add_u64 v[168:169], v[166:167], 0, vcc
	s_waitcnt vmcnt(8)
	v_permlane16_swap_b32_e32 v106, v98
	v_permlane16_swap_b32_e32 v107, v99
	v_permlane16_swap_b32_e32 v108, v100
	v_permlane16_swap_b32_e32 v109, v101
	v_permlane16_swap_b32_e32 v102, v94
	v_permlane16_swap_b32_e32 v103, v95
	v_permlane16_swap_b32_e32 v104, v96
	v_permlane16_swap_b32_e32 v105, v97
	v_mul_f32_e32 v188, v98, v1
	v_mul_f32_e32 v1, v106, v1
	v_mul_f32_e32 v189, v99, v3
	v_mul_f32_e32 v3, v107, v3
	v_mul_f32_e32 v190, v100, v5
	v_mul_f32_e32 v5, v108, v5
	v_mul_f32_e32 v191, v101, v7
	v_mul_f32_e32 v7, v109, v7
	v_mul_f32_e32 v192, v94, v177
	v_mul_f32_e32 v177, v102, v177
	v_mul_f32_e32 v193, v95, v179
	v_mul_f32_e32 v179, v103, v179
	v_mul_f32_e32 v194, v96, v173
	v_mul_f32_e32 v173, v104, v173
	v_mul_f32_e32 v195, v97, v175
	v_mul_f32_e32 v175, v105, v175
	v_fma_f32 v106, v106, v0, -v188
	v_fma_f32 v98, v98, v0, v1
	v_fma_f32 v107, v107, v2, -v189
	v_fma_f32 v99, v99, v2, v3
	v_fma_f32 v108, v108, v4, -v190
	v_fma_f32 v100, v100, v4, v5
	v_fma_f32 v109, v109, v6, -v191
	v_fma_f32 v101, v101, v6, v7
	v_fma_f32 v102, v102, v176, -v192
	v_fma_f32 v94, v94, v176, v177
	v_fma_f32 v103, v103, v178, -v193
	v_fma_f32 v95, v95, v178, v179
	v_fma_f32 v104, v104, v172, -v194
	v_fma_f32 v96, v96, v172, v173
	v_fma_f32 v105, v105, v174, -v195
	v_fma_f32 v97, v97, v174, v175
	v_permlane16_swap_b32_e32 v106, v98
	v_permlane16_swap_b32_e32 v107, v99
	v_permlane16_swap_b32_e32 v108, v100
	v_permlane16_swap_b32_e32 v109, v101
	v_permlane16_swap_b32_e32 v102, v94
	v_permlane16_swap_b32_e32 v103, v95
	v_permlane16_swap_b32_e32 v104, v96
	v_permlane16_swap_b32_e32 v105, v97
	s_cmp_lt_u32 s48, 3
	s_cbranch_scc0 .Lz_rl_noqs2
	v_mul_f32_e32 v106, s8, v106
	v_mul_f32_e32 v107, s8, v107
	v_mul_f32_e32 v108, s8, v108
	v_mul_f32_e32 v109, s8, v109
	v_mul_f32_e32 v102, s8, v102
	v_mul_f32_e32 v103, s8, v103
	v_mul_f32_e32 v104, s8, v104
	v_mul_f32_e32 v105, s8, v105
	v_mul_f32_e32 v98, s8, v98
	v_mul_f32_e32 v99, s8, v99
	v_mul_f32_e32 v100, s8, v100
	v_mul_f32_e32 v101, s8, v101
	v_mul_f32_e32 v94, s8, v94
	v_mul_f32_e32 v95, s8, v95
	v_mul_f32_e32 v96, s8, v96
	v_mul_f32_e32 v97, s8, v97

; __device__ __forceinline__ unsigned cvt_pk_bf16(float lo, float hi) { unsigned r; asm volatile("v_cvt_pk_bf16_f32 %0, %1, %2" : "=v"(r) : "v"(lo), "v"(hi)); return r; }
;     __device__ __forceinline__ void operator()(const f32x4 (&acc)[2][2][4][2], const Unit& u, int wr, int wc, int fr, int fq) const {
;     ...
;                 if (do_rope) {
;                     const f32x4* cs = (const f32x4*)(rope + (size_t)(isP ? t : 4096) * 16);
; #pragma unroll
;                     for (int q = 0; q < 4; ++q) { const f32x4 c = cs[q]; cosv[2 * q] = c[0]; sinv[2 * q] = c[1]; cosv[2 * q + 1] = c[2]; sinv[2 * q + 1] = c[3]; }
;                 }
; #pragma unroll
;                 for (int bj = 0; bj < 2; ++bj) {
;                     f32x4 v0 = acc[ai][bj][m][0], v1 = acc[ai][bj][m][1];
;                     const int cit = bj * HALF + wc * 32 + fq * 8;
;                     if (do_rope) {
; #pragma unroll
;                         for (int j = 0; j < 4; ++j) {
;                             const float p0 = __shfl_xor(v0[j], 16), p1 = __shfl_xor(v1[j], 16);
;                             const float r0 = v0[j] * cosv[j] + sgn * p0 * sinv[j], r1 = v1[j] * cosv[4 + j] + sgn * p1 * sinv[4 + j];
;                             v0[j] = fq < 2 ? r0 : v0[j]; v1[j] = fq < 2 ? r1 : v1[j];
;                         }
;                     }
;                     if (pn < 3) { v0 = v0 * QSCALE; v1 = v1 * QSCALE; }
;                     u32x4 w; w.x = cvt_pk_bf16(v0[0], v0[1]); w.y = cvt_pk_bf16(v0[2], v0[3]); w.z = cvt_pk_bf16(v1[0], v1[1]); w.w = cvt_pk_bf16(v1[2], v1[3]);
;                     *(u32x4*)(Z + (size_t)row * NZ + pn * BM + cit) = w;
;                     if (is_kv) {
;                         float* dst = nullptr;
;                         if (isP && t >= 4096 - W) dst = out + okp + ((size_t)(b * W + t - (4096 - W)) * 2 + kvsel) * 256 + cit;
;                         else if (isS) dst = out + oks + ((size_t)(b * W + W - 1) * 2 + kvsel) * 256 + cit;
;                         if (dst) { *(f32x4*)dst = v0; *(f32x4*)(dst + 4) = v1; }
.Lz_rl_nokv2:
	s_mov_b32 vcc_lo, 0xc6000
	s_mov_b32 vcc_hi, 0
	v_lshl_add_u64 v[168:169], v[166:167], 0, vcc
	s_waitcnt vmcnt(4)
	v_permlane16_swap_b32_e32 v86, v78
	v_permlane16_swap_b32_e32 v87, v79
	v_permlane16_swap_b32_e32 v88, v80
	v_permlane16_swap_b32_e32 v89, v81
	v_permlane16_swap_b32_e32 v90, v82
	v_permlane16_swap_b32_e32 v91, v83
	v_permlane16_swap_b32_e32 v92, v84
	v_permlane16_swap_b32_e32 v93, v85
	v_mul_f32_e32 v188, v78, v135
	v_mul_f32_e32 v135, v86, v135
	v_mul_f32_e32 v189, v79, v137
	v_mul_f32_e32 v137, v87, v137
	v_mul_f32_e32 v190, v80, v139
	v_mul_f32_e32 v139, v88, v139
	v_mul_f32_e32 v191, v81, v141
	v_mul_f32_e32 v141, v89, v141
	v_mul_f32_e32 v192, v82, v127
	v_mul_f32_e32 v127, v90, v127
	v_mul_f32_e32 v193, v83, v129
	v_mul_f32_e32 v129, v91, v129
	v_mul_f32_e32 v194, v84, v131
	v_mul_f32_e32 v131, v92, v131
	v_mul_f32_e32 v195, v85, v133
	v_mul_f32_e32 v133, v93, v133
	v_fma_f32 v86, v86, v134, -v188
	v_fma_f32 v78, v78, v134, v135
	v_fma_f32 v87, v87, v136, -v189
	v_fma_f32 v79, v79, v136, v137
	v_fma_f32 v88, v88, v138, -v190
	v_fma_f32 v80, v80, v138, v139
	v_fma_f32 v89, v89, v140, -v191
	v_fma_f32 v81, v81, v140, v141
	v_fma_f32 v90, v90, v126, -v192
	v_fma_f32 v82, v82, v126, v127
	v_fma_f32 v91, v91, v128, -v193
	v_fma_f32 v83, v83, v128, v129
	v_fma_f32 v92, v92, v130, -v194
	v_fma_f32 v84, v84, v130, v131
	v_fma_f32 v93, v93, v132, -v195
	v_fma_f32 v85, v85, v132, v133
	v_permlane16_swap_b32_e32 v86, v78
	v_permlane16_swap_b32_e32 v87, v79
	v_permlane16_swap_b32_e32 v88, v80
	v_permlane16_swap_b32_e32 v89, v81
	v_permlane16_swap_b32_e32 v90, v82
	v_permlane16_swap_b32_e32 v91, v83
	v_permlane16_swap_b32_e32 v92, v84
	v_permlane16_swap_b32_e32 v93, v85
	s_cmp_lt_u32 s48, 3
	s_cbranch_scc0 .Lz_rl_noqs3
	v_mul_f32_e32 v86, s8, v86
	v_mul_f32_e32 v87, s8, v87
	v_mul_f32_e32 v88, s8, v88
	v_mul_f32_e32 v89, s8, v89
	v_mul_f32_e32 v90, s8, v90
	v_mul_f32_e32 v91, s8, v91
	v_mul_f32_e32 v92, s8, v92
	v_mul_f32_e32 v93, s8, v93
	v_mul_f32_e32 v78, s8, v78
	v_mul_f32_e32 v79, s8, v79
	v_mul_f32_e32 v80, s8, v80
	v_mul_f32_e32 v81, s8, v81
	v_mul_f32_e32 v82, s8, v82
	v_mul_f32_e32 v83, s8, v83
	v_mul_f32_e32 v84, s8, v84
	v_mul_f32_e32 v85, s8, v85
.Lz_rl_noqs3:
	v_cvt_pk_bf16_f32 v188, v86, v87
	v_cvt_pk_bf16_f32 v189, v88, v89
	v_cvt_pk_bf16_f32 v190, v90, v91
	v_cvt_pk_bf16_f32 v191, v92, v93
	global_store_dwordx4 v[168:169], v[188:191], off
	v_cvt_pk_bf16_f32 v192, v78, v79
	v_cvt_pk_bf16_f32 v193, v80, v81
	v_cvt_pk_bf16_f32 v194, v82, v83
	v_cvt_pk_bf16_f32 v195, v84, v85
	global_store_dwordx4 v[168:169], v[192:195], off offset:256
	s_cmp_lg_u32 s44, 0
	s_cbranch_scc0 .Lz_rl_nokv3
	v_add_u32_e32 v165, 0x18000, v164
	global_store_dwordx4 v165, v[86:89], s[96:97]
	global_store_dwordx4 v165, v[90:93], s[96:97] offset:16
	global_store_dwordx4 v165, v[78:81], s[96:97] offset:512
	global_store_dwordx4 v165, v[82:85], s[96:97] offset:528
.Lz_rl_nokv3:
	s_branch .LBB0_297
.Lz_rw_hi:
	s_movk_i32 s98, 0x80
	v_mad_u32_u24 v8, v171, s98, v170
	global_load_dwordx4 v[196:199], v8, s[34:35]
	global_load_dwordx4 v[200:203], v8, s[34:35] offset:16
	global_load_dwordx4 v[204:207], v8, s[34:35] offset:32
	global_load_dwordx4 v[208:211], v8, s[34:35] offset:48
	s_movk_i32 s98, 0x90
	v_mad_u32_u24 v9, v171, s98, v170
	global_load_dwordx4 v[212:215], v9, s[34:35]
	global_load_dwordx4 v[216:219], v9, s[34:35] offset:16
	global_load_dwordx4 v[220:223], v9, s[34:35] offset:32
	global_load_dwordx4 v[224:227], v9, s[34:35] offset:48
	s_movk_i32 s98, 0xa0
	v_mad_u32_u24 v8, v171, s98, v170
	global_load_dwordx4 v[0:3], v8, s[34:35]
	global_load_dwordx4 v[4:7], v8, s[34:35] offset:16
	global_load_dwordx4 v[176:179], v8, s[34:35] offset:32
	global_load_dwordx4 v[172:175], v8, s[34:35] offset:48
	s_mov_b32 vcc_lo, 0x210000
	s_mov_b32 vcc_hi, 0
	v_lshl_add_u64 v[168:169], v[166:167], 0, vcc
	s_waitcnt vmcnt(8)
	v_permlane16_swap_b32_e32 v70, v62
	v_permlane16_swap_b32_e32 v71, v63
	v_permlane16_swap_b32_e32 v72, v64
	v_permlane16_swap_b32_e32 v73, v65
	v_permlane16_swap_b32_e32 v74, v66
	v_permlane16_swap_b32_e32 v75, v67
	v_permlane16_swap_b32_e32 v76, v68
	v_permlane16_swap_b32_e32 v77, v69
	v_mul_f32_e32 v188, v62, v197
	v_mul_f32_e32 v197, v70, v197
	v_mul_f32_e32 v189, v63, v199
	v_mul_f32_e32 v199, v71, v199
	v_mul_f32_e32 v190, v64, v201
	v_mul_f32_e32 v201, v72, v201
	v_mul_f32_e32 v191, v65, v203
	v_mul_f32_e32 v203, v73, v203
	v_mul_f32_e32 v192, v66, v205
	v_mul_f32_e32 v205, v74, v205
	v_mul_f32_e32 v193, v67, v207
	v_mul_f32_e32 v207, v75, v207
	v_mul_f32_e32 v194, v68, v209
	v_mul_f32_e32 v209, v76, v209
	v_mul_f32_e32 v195, v69, v211
	v_mul_f32_e32 v211, v77, v211
	v_fma_f32 v70, v70, v196, -v188
	v_fma_f32 v62, v62, v196, v197
	v_fma_f32 v71, v71, v198, -v189
	v_fma_f32 v63, v63, v198, v199
	v_fma_f32 v72, v72, v200, -v190
	v_fma_f32 v64, v64, v200, v201
	v_fma_f32 v73, v73, v202, -v191
	v_fma_f32 v65, v65, v202, v203
	v_fma_f32 v74, v74, v204, -v192
	v_fma_f32 v66, v66, v204, v205
	v_fma_f32 v75, v75, v206, -v193
	v_fma_f32 v67, v67, v206, v207
	v_fma_f32 v76, v76, v208, -v194
	v_fma_f32 v68, v68, v208, v209
	v_fma_f32 v77, v77, v210, -v195
	v_fma_f32 v69, v69, v210, v211
	v_permlane16_swap_b32_e32 v70, v62
	v_permlane16_swap_b32_e32 v71, v63
	v_permlane16_swap_b32_e32 v72, v64
	v_permlane16_swap_b32_e32 v73, v65
	v_permlane16_swap_b32_e32 v74, v66
	v_permlane16_swap_b32_e32 v75, v67
	v_permlane16_swap_b32_e32 v76, v68
	v_permlane16_swap_b32_e32 v77, v69
	s_cmp_lt_u32 s48, 3
	s_cbranch_scc0 .Lz_rh_noqs4
	v_mul_f32_e32 v70, s8, v70
	v_mul_f32_e32 v71, s8, v71
	v_mul_f32_e32 v72, s8, v72
	v_mul_f32_e32 v73, s8, v73
	v_mul_f32_e32 v74, s8, v74
	v_mul_f32_e32 v75, s8, v75
	v_mul_f32_e32 v76, s8, v76
	v_mul_f32_e32 v77, s8, v77
	v_mul_f32_e32 v62, s8, v62
	v_mul_f32_e32 v63, s8, v63
	v_mul_f32_e32 v64, s8, v64
	v_mul_f32_e32 v65, s8, v65
	v_mul_f32_e32 v66, s8, v66
	v_mul_f32_e32 v67, s8, v67
	v_mul_f32_e32 v68, s8, v68
	v_mul_f32_e32 v69, s8, v69

;     __device__ __forceinline__ void operator()(const f32x4 (&acc)[2][2][4][2], const Unit& u, int wr, int wc, int fr, int fq) const {
;     ...
;                 const int row = u.pm * BM + ai * HALF + wr * 64 + m * 16 + fr;
;                 const bool isP = row < MP, isS = (row >= MP) && (row < MT);
;                 const int b = isP ? (row >> 12) : (row - MP);
;                 const int t = row & 4095;
;                 float cosv[8], sinv[8];
;                 if (do_rope) {
;                     const f32x4* cs = (const f32x4*)(rope + (size_t)(isP ? t : 4096) * 16);
; #pragma unroll
;                     for (int q = 0; q < 4; ++q) { const f32x4 c = cs[q]; cosv[2 * q] = c[0]; sinv[2 * q] = c[1]; cosv[2 * q + 1] = c[2]; sinv[2 * q + 1] = c[3]; }
;                 }
; #pragma unroll
;                 for (int bj = 0; bj < 2; ++bj) {
;                     f32x4 v0 = acc[ai][bj][m][0], v1 = acc[ai][bj][m][1];
;                     const int cit = bj * HALF + wc * 32 + fq * 8;
;                     if (do_rope) {
; #pragma unroll
;                         for (int j = 0; j < 4; ++j) {
;                             const float p0 = __shfl_xor(v0[j], 16), p1 = __shfl_xor(v1[j], 16);
;                             const float r0 = v0[j] * cosv[j] + sgn * p0 * sinv[j], r1 = v1[j] * cosv[4 + j] + sgn * p1 * sinv[4 + j];
;                             v0[j] = fq < 2 ? r0 : v0[j]; v1[j] = fq < 2 ? r1 : v1[j];
;                         }
;                     }
;                     if (pn < 3) { v0 = v0 * QSCALE; v1 = v1 * QSCALE; }
.Lz_rh_nokv4:
	s_movk_i32 s98, 0xb0
	v_mad_u32_u24 v9, v171, s98, v170
	global_load_dwordx4 v[70:73], v9, s[34:35]
	global_load_dwordx4 v[74:77], v9, s[34:35] offset:16
	global_load_dwordx4 v[62:65], v9, s[34:35] offset:32
	global_load_dwordx4 v[66:69], v9, s[34:35] offset:48
	s_mov_b32 vcc_lo, 0x252000
	s_mov_b32 vcc_hi, 0
	v_lshl_add_u64 v[168:169], v[166:167], 0, vcc
	s_waitcnt vmcnt(10)
	v_permlane16_swap_b32_e32 v54, v42
	v_permlane16_swap_b32_e32 v55, v43
	v_permlane16_swap_b32_e32 v56, v44
	v_permlane16_swap_b32_e32 v57, v45
	v_permlane16_swap_b32_e32 v58, v46
	v_permlane16_swap_b32_e32 v59, v47
	v_permlane16_swap_b32_e32 v60, v48
	v_permlane16_swap_b32_e32 v61, v49
	v_mul_f32_e32 v188, v42, v213
	v_mul_f32_e32 v213, v54, v213
	v_mul_f32_e32 v189, v43, v215
	v_mul_f32_e32 v215, v55, v215
	v_mul_f32_e32 v190, v44, v217
	v_mul_f32_e32 v217, v56, v217
	v_mul_f32_e32 v191, v45, v219
	v_mul_f32_e32 v219, v57, v219
	v_mul_f32_e32 v192, v46, v221
	v_mul_f32_e32 v221, v58, v221
	v_mul_f32_e32 v193, v47, v223
	v_mul_f32_e32 v223, v59, v223
	v_mul_f32_e32 v194, v48, v225
	v_mul_f32_e32 v225, v60, v225
	v_mul_f32_e32 v195, v49, v227
	v_mul_f32_e32 v227, v61, v227
	v_fma_f32 v54, v54, v212, -v188
	v_fma_f32 v42, v42, v212, v213
	v_fma_f32 v55, v55, v214, -v189
	v_fma_f32 v43, v43, v214, v215
	v_fma_f32 v56, v56, v216, -v190
	v_fma_f32 v44, v44, v216, v217
	v_fma_f32 v57, v57, v218, -v191
	v_fma_f32 v45, v45, v218, v219
	v_fma_f32 v58, v58, v220, -v192
	v_fma_f32 v46, v46, v220, v221
	v_fma_f32 v59, v59, v222, -v193
	v_fma_f32 v47, v47, v222, v223
	v_fma_f32 v60, v60, v224, -v194
	v_fma_f32 v48, v48, v224, v225
	v_fma_f32 v61, v61, v226, -v195
	v_fma_f32 v49, v49, v226, v227
	v_permlane16_swap_b32_e32 v54, v42
	v_permlane16_swap_b32_e32 v55, v43
	v_permlane16_swap_b32_e32 v56, v44
	v_permlane16_swap_b32_e32 v57, v45
	v_permlane16_swap_b32_e32 v58, v46
	v_permlane16_swap_b32_e32 v59, v47
	v_permlane16_swap_b32_e32 v60, v48
	v_permlane16_swap_b32_e32 v61, v49
	s_cmp_lt_u32 s48, 3
	s_cbranch_scc0 .Lz_rh_noqs5
	v_mul_f32_e32 v54, s8, v54
	v_mul_f32_e32 v55, s8, v55
	v_mul_f32_e32 v56, s8, v56
	v_mul_f32_e32 v57, s8, v57
	v_mul_f32_e32 v58, s8, v58
	v_mul_f32_e32 v59, s8, v59
	v_mul_f32_e32 v60, s8, v60
	v_mul_f32_e32 v61, s8, v61
	v_mul_f32_e32 v42, s8, v42
	v_mul_f32_e32 v43, s8, v43
	v_mul_f32_e32 v44, s8, v44
	v_mul_f32_e32 v45, s8, v45
	v_mul_f32_e32 v46, s8, v46
	v_mul_f32_e32 v47, s8, v47
	v_mul_f32_e32 v48, s8, v48
	v_mul_f32_e32 v49, s8, v49

;     __device__ __forceinline__ void operator()(const f32x4 (&acc)[2][2][4][2], const Unit& u, int wr, int wc, int fr, int fq) const {
;     ...
;                 const int row = u.pm * BM + ai * HALF + wr * 64 + m * 16 + fr;
;                 const bool isP = row < MP, isS = (row >= MP) && (row < MT);
;                 const int b = isP ? (row >> 12) : (row - MP);
;                 const int t = row & 4095;
;                 float cosv[8], sinv[8];
;                 if (do_rope) {
;                     const f32x4* cs = (const f32x4*)(rope + (size_t)(isP ? t : 4096) * 16);
; #pragma unroll
;                     for (int q = 0; q < 4; ++q) { const f32x4 c = cs[q]; cosv[2 * q] = c[0]; sinv[2 * q] = c[1]; cosv[2 * q + 1] = c[2]; sinv[2 * q + 1] = c[3]; }
;                 }
; #pragma unroll
;                 for (int bj = 0; bj < 2; ++bj) {
;                     f32x4 v0 = acc[ai][bj][m][0], v1 = acc[ai][bj][m][1];
;                     const int cit = bj * HALF + wc * 32 + fq * 8;
;                     if (do_rope) {
; #pragma unroll
;                         for (int j = 0; j < 4; ++j) {
;                             const float p0 = __shfl_xor(v0[j], 16), p1 = __shfl_xor(v1[j], 16);
;                             const float r0 = v0[j] * cosv[j] + sgn * p0 * sinv[j], r1 = v1[j] * cosv[4 + j] + sgn * p1 * sinv[4 + j];
;                             v0[j] = fq < 2 ? r0 : v0[j]; v1[j] = fq < 2 ? r1 : v1[j];
;                         }
;                     }
;                     if (pn < 3) { v0 = v0 * QSCALE; v1 = v1 * QSCALE; }
.Lz_rh_nokv5:
	s_mov_b32 vcc_lo, 0x294000
	s_mov_b32 vcc_hi, 0
	v_lshl_add_u64 v[168:169], v[166:167], 0, vcc
	s_waitcnt vmcnt(8)
	v_permlane16_swap_b32_e32 v38, v30
	v_permlane16_swap_b32_e32 v39, v31
	v_permlane16_swap_b32_e32 v40, v32
	v_permlane16_swap_b32_e32 v41, v33
	v_permlane16_swap_b32_e32 v34, v26
	v_permlane16_swap_b32_e32 v35, v27
	v_permlane16_swap_b32_e32 v36, v28
	v_permlane16_swap_b32_e32 v37, v29
	v_mul_f32_e32 v188, v30, v1
	v_mul_f32_e32 v1, v38, v1
	v_mul_f32_e32 v189, v31, v3
	v_mul_f32_e32 v3, v39, v3
	v_mul_f32_e32 v190, v32, v5
	v_mul_f32_e32 v5, v40, v5
	v_mul_f32_e32 v191, v33, v7
	v_mul_f32_e32 v7, v41, v7
	v_mul_f32_e32 v192, v26, v177
	v_mul_f32_e32 v177, v34, v177
	v_mul_f32_e32 v193, v27, v179
	v_mul_f32_e32 v179, v35, v179
	v_mul_f32_e32 v194, v28, v173
	v_mul_f32_e32 v173, v36, v173
	v_mul_f32_e32 v195, v29, v175
	v_mul_f32_e32 v175, v37, v175
	v_fma_f32 v38, v38, v0, -v188
	v_fma_f32 v30, v30, v0, v1
	v_fma_f32 v39, v39, v2, -v189
	v_fma_f32 v31, v31, v2, v3
	v_fma_f32 v40, v40, v4, -v190
	v_fma_f32 v32, v32, v4, v5
	v_fma_f32 v41, v41, v6, -v191
	v_fma_f32 v33, v33, v6, v7
	v_fma_f32 v34, v34, v176, -v192
	v_fma_f32 v26, v26, v176, v177
	v_fma_f32 v35, v35, v178, -v193
	v_fma_f32 v27, v27, v178, v179
	v_fma_f32 v36, v36, v172, -v194
	v_fma_f32 v28, v28, v172, v173
	v_fma_f32 v37, v37, v174, -v195
	v_fma_f32 v29, v29, v174, v175
	v_permlane16_swap_b32_e32 v38, v30
	v_permlane16_swap_b32_e32 v39, v31
	v_permlane16_swap_b32_e32 v40, v32
	v_permlane16_swap_b32_e32 v41, v33
	v_permlane16_swap_b32_e32 v34, v26
	v_permlane16_swap_b32_e32 v35, v27
	v_permlane16_swap_b32_e32 v36, v28
	v_permlane16_swap_b32_e32 v37, v29
	s_cmp_lt_u32 s48, 3
	s_cbranch_scc0 .Lz_rh_noqs6
	v_mul_f32_e32 v38, s8, v38
	v_mul_f32_e32 v39, s8, v39
	v_mul_f32_e32 v40, s8, v40
	v_mul_f32_e32 v41, s8, v41
	v_mul_f32_e32 v34, s8, v34
	v_mul_f32_e32 v35, s8, v35
	v_mul_f32_e32 v36, s8, v36
	v_mul_f32_e32 v37, s8, v37
	v_mul_f32_e32 v30, s8, v30
	v_mul_f32_e32 v31, s8, v31
	v_mul_f32_e32 v32, s8, v32
	v_mul_f32_e32 v33, s8, v33
	v_mul_f32_e32 v26, s8, v26
	v_mul_f32_e32 v27, s8, v27
	v_mul_f32_e32 v28, s8, v28
	v_mul_f32_e32 v29, s8, v29
